# peer top-k: per-row top-16 stage hand-written (tournament arg-max), next item's query fragments prefetched during the selection stages
# speedup vs baseline: 1.0153x; 1.0052x over previous
; #define MFMA(a, b, c) __builtin_amdgcn_mfma_f32_32x32x16_bf16((a), (b), (c), 0, 0, 0)
; DI f32x16 zero16() { f32x16 z; for (int i = 0; i < 16; ++i) z[i] = 0.f; return z; }
; DI void peer_topk_item(const Params& p, int tt128, int head, char* smem) {
;     ...
;   const int tid = threadIdx.x, lane = tid & 63, wave = tid >> 6, lr = lane & 31, lh = lane >> 5;
;   const int tok0 = tt128 * 128;
;   {
;     const int half = wave >> 2, kt = wave & 3;
;     bf16x8 af[8];
; #pragma unroll
;     for (int ks = 0; ks < 8; ++ks) af[ks] = ldg8(sk + (size_t)half * 16384 + (kt * 32 + lr) * 128 + ks * 16 + lh * 8);
; #pragma unroll 1
;     for (int tt = 0; tt < 4; ++tt) {
;       f32x16 acc = zero16();
;       const u16* brow = pq + (((((size_t)(tok0 >> 5) + tt) * 8 + head) * 2 + half) * 8) * 512 + lane * 8;
; #pragma unroll
;       for (int ks = 0; ks < 8; ++ks) acc = MFMA(af[ks], ldg8(brow + ks * 512), acc);
; __global__ void __launch_bounds__(512) fwd_megakernel(Params p) {
;     ...
;   for (int it = blockIdx.x; it < 2048; it += G) peer_topk_item(p, it >> 3, it & 7, smem);
.LBB0_960:
	s_or_b64 exec, exec, s[0:1]
	v_readlane_b32 s0, v255, 39
	v_readlane_b32 s1, v255, 40
	s_and_b64 vcc, exec, s[0:1]
	s_waitcnt lgkmcnt(0)
	s_barrier
	s_cbranch_vccnz .LBB0_970
	v_bfe_u32 v4, v166, 6, 2
	v_lshlrev_b32_e32 v0, 15, v141
	v_mov_b32_e32 v1, 0
	v_lshl_add_u64 v[2:3], s[96:97], 0, v[0:1]
	v_lshl_or_b32 v0, v4, 13, v142
	v_lshl_add_u64 v[2:3], v[2:3], 0, v[0:1]
	v_mov_b32_e32 v171, v1
	v_lshl_add_u64 v[2:3], v[2:3], 0, v[170:171]
	s_mov_b64 s[0:1], 0xa440000
	v_lshl_add_u64 v[48:49], v[2:3], 0, s[0:1]
	v_lshlrev_b32_e32 v2, 4, v166
	s_movk_i32 s0, 0x80
	v_lshlrev_b32_e32 v0, 7, v4
	v_cmp_gt_u32_e64 s[6:7], s0, v166
	v_or_b32_e32 v4, 0x800, v2
	v_add_u32_e32 v57, 0x24400, v2
	v_add_u32_e32 v58, 0x24c00, v2
	v_mul_u32_u24_e32 v2, 0x204, v168
	s_mov_b32 s0, 0x10200
	v_mad_u32_u24 v2, v141, s0, v2
	v_add3_u32 v59, v2, v0, v211
	v_lshlrev_b32_e32 v0, 5, v166
	s_movk_i32 s0, 0x6000
	v_mov_b32_e32 v3, 0x20400
	s_add_u32 s48, s96, 0x1000000
	v_and_or_b32 v0, v0, s0, v164
	v_mul_u32_u24_e32 v54, 0x204, v166
	v_lshl_add_u32 v55, v166, 6, v3
	v_lshl_add_u32 v56, v4, 2, v3
	s_addc_u32 s49, s97, 0
	v_lshl_add_u64 v[50:51], s[96:97], 0, v[0:1]
	s_mov_b32 s51, 0
	v_mov_b32_e32 v60, 0xff800000
	v_mov_b32_e32 v61, 0x41
	v_mov_b32_e32 v62, 0x50
	v_mov_b32_e32 v63, 0x51
	v_mov_b32_e32 v64, 0x52
	v_mov_b32_e32 v65, 0x42
	v_mov_b32_e32 v66, 0x43
	v_mov_b32_e32 v67, 0x53
	v_mov_b32_e32 v68, 0x54
	v_mov_b32_e32 v69, 0x44
	v_mov_b32_e32 v70, 0x45
	v_mov_b32_e32 v71, 0x55
	v_mov_b32_e32 v72, 0x56
	v_mov_b32_e32 v73, 0x46
	v_mov_b32_e32 v74, 0x47
	v_mov_b32_e32 v75, 0x57
	v_mov_b32_e32 v76, 0x58
	v_mov_b32_e32 v77, 0x48
	v_mov_b32_e32 v78, 0x49
	v_mov_b32_e32 v79, 0x59
	v_mov_b32_e32 v80, 0x5a
	v_mov_b32_e32 v81, 0x4a
	v_mov_b32_e32 v82, 0x4b
	v_mov_b32_e32 v83, 0x5b
	v_mov_b32_e32 v84, 0x5c
	v_mov_b32_e32 v85, 0x4c
	v_mov_b32_e32 v86, 0x4d
	v_mov_b32_e32 v87, 0x5d
	v_mov_b32_e32 v88, 0x5e
	v_mov_b32_e32 v89, 0x4e
	v_mov_b32_e32 v90, 0x4f
	v_mov_b32_e32 v91, 0x5f
	v_mov_b32_e32 v92, 0x60
	v_mov_b32_e32 v93, 0x61
	v_mov_b32_e32 v94, 0x70
	v_mov_b32_e32 v95, 0x71
	v_mov_b32_e32 v96, 0x72
	v_mov_b32_e32 v97, 0x62
	v_mov_b32_e32 v98, 0x63
	v_mov_b32_e32 v99, 0x73
	v_mov_b32_e32 v100, 0x74
	v_mov_b32_e32 v101, 0x64
	v_mov_b32_e32 v102, 0x65
	v_mov_b32_e32 v103, 0x75
	v_mov_b32_e32 v104, 0x76
	v_mov_b32_e32 v105, 0x66
	v_mov_b32_e32 v106, 0x67
	v_mov_b32_e32 v107, 0x77
	v_mov_b32_e32 v108, 0x78
	v_mov_b32_e32 v109, 0x68
	v_mov_b32_e32 v110, 0x69
	v_mov_b32_e32 v111, 0x79
	v_mov_b32_e32 v112, 0x7a
	v_mov_b32_e32 v113, 0x6a
	v_mov_b32_e32 v114, 0x6b
	v_mov_b32_e32 v115, 0x7b
	v_mov_b32_e32 v116, 0x7c
	v_mov_b32_e32 v117, 0x6c
	v_mov_b32_e32 v118, 0x6d
	v_mov_b32_e32 v119, 0x7d
	v_mov_b32_e32 v120, 0x7e
	v_mov_b32_e32 v121, 0x6e
	v_mov_b32_e32 v122, 0x6f
	v_mov_b32_e32 v123, 0x7f
	s_mov_b32 s3, s2
	s_and_b32 s0, s3, 7
	s_ashr_i32 s10, s2, 3
	s_lshl_b32 s4, s0, 14
	s_lshl_b32 s0, s10, 2
	s_ashr_i32 s1, s0, 31
	s_lshl_b64 s[0:1], s[0:1], 17
	s_or_b32 s0, s0, s4
	v_lshl_add_u64 v[142:143], v[50:51], 0, s[0:1]
	s_mov_b32 s4, 0x16800000
	s_mov_b32 s5, 0
	s_mov_b64 s[8:9], 0x20000
	v_lshl_add_u64 v[142:143], v[142:143], 0, s[4:5]
	s_movk_i32 s10, 0x1000
	s_mov_b32 s11, 0
	v_lshl_add_u64 v[144:145], v[142:143], 0, s[10:11]
	v_lshl_add_u64 v[146:147], v[142:143], 0, s[8:9]
	v_lshl_add_u64 v[148:149], v[144:145], 0, s[8:9]
	global_load_dwordx4 v[168:171], v[142:143], off
	global_load_dwordx4 v[172:175], v[142:143], off offset:1024
	global_load_dwordx4 v[176:179], v[142:143], off offset:2048
	global_load_dwordx4 v[180:183], v[142:143], off offset:3072
	global_load_dwordx4 v[184:187], v[144:145], off
	global_load_dwordx4 v[188:191], v[144:145], off offset:1024
	global_load_dwordx4 v[192:195], v[144:145], off offset:2048
	global_load_dwordx4 v[196:199], v[144:145], off offset:3072
	global_load_dwordx4 v[200:203], v[146:147], off
	global_load_dwordx4 v[204:207], v[146:147], off offset:1024
	global_load_dwordx4 v[208:211], v[146:147], off offset:2048
	global_load_dwordx4 v[212:215], v[146:147], off offset:3072
	global_load_dwordx4 v[216:219], v[148:149], off
	global_load_dwordx4 v[220:223], v[148:149], off offset:1024
	global_load_dwordx4 v[224:227], v[148:149], off offset:2048
	global_load_dwordx4 v[228:231], v[148:149], off offset:3072
	s_branch .LBB0_963

; #define MFMA(a, b, c) __builtin_amdgcn_mfma_f32_32x32x16_bf16((a), (b), (c), 0, 0, 0)
; DI int crow(int i, int h) { return (i & 3) + 8 * (i >> 2) + 4 * h; }
; DI f32x16 zero16() { f32x16 z; for (int i = 0; i < 16; ++i) z[i] = 0.f; return z; }
; DI void peer_topk_item(const Params& p, int tt128, int head, char* smem) {
;     ...
; #pragma unroll 1
;     for (int tt = 0; tt < 4; ++tt) {
;       f32x16 acc = zero16();
;       const u16* brow = pq + (((((size_t)(tok0 >> 5) + tt) * 8 + head) * 2 + half) * 8) * 512 + lane * 8;
; #pragma unroll
;       for (int ks = 0; ks < 8; ++ks) acc = MFMA(af[ks], ldg8(brow + ks * 512), acc);
; #pragma unroll
;       for (int i = 0; i < 16; ++i) sc[(half * 128 + tt * 32 + lr) * 129 + kt * 32 + crow(i, lh)] = acc[i];
;     }
.LBB0_964:
	s_mov_b32 s4, 0x16800000
	s_mov_b32 s5, 0
	s_mov_b64 s[8:9], 0x20000
	v_lshl_add_u64 v[142:143], v[52:53], 0, s[4:5]
	s_movk_i32 s10, 0x1000
	s_mov_b32 s11, 0
	v_lshl_add_u64 v[144:145], v[142:143], 0, s[10:11]
	v_lshl_add_u64 v[146:147], v[142:143], 0, s[8:9]
	v_lshl_add_u64 v[148:149], v[144:145], 0, s[8:9]
	v_lshl_add_u64 v[150:151], v[146:147], 0, s[8:9]
	v_lshl_add_u64 v[152:153], v[148:149], 0, s[8:9]
	v_lshl_add_u64 v[154:155], v[150:151], 0, s[8:9]
	v_lshl_add_u64 v[156:157], v[152:153], 0, s[8:9]
	s_waitcnt vmcnt(7)
	v_mfma_f32_32x32x16_bf16 v[0:15], v[16:19], v[168:171], 0
	global_load_dwordx4 v[168:171], v[150:151], off
	s_waitcnt vmcnt(7)
	v_mfma_f32_32x32x16_bf16 v[0:15], v[20:23], v[172:175], v[0:15]
	global_load_dwordx4 v[172:175], v[150:151], off offset:1024
	s_waitcnt vmcnt(7)
	v_mfma_f32_32x32x16_bf16 v[0:15], v[24:27], v[176:179], v[0:15]
	global_load_dwordx4 v[176:179], v[150:151], off offset:2048
	s_waitcnt vmcnt(7)
	v_mfma_f32_32x32x16_bf16 v[0:15], v[28:31], v[180:183], v[0:15]
	global_load_dwordx4 v[180:183], v[150:151], off offset:3072
	s_waitcnt vmcnt(7)
	v_mfma_f32_32x32x16_bf16 v[0:15], v[32:35], v[184:187], v[0:15]
	global_load_dwordx4 v[184:187], v[152:153], off
	s_waitcnt vmcnt(7)
	v_mfma_f32_32x32x16_bf16 v[0:15], v[36:39], v[188:191], v[0:15]
	global_load_dwordx4 v[188:191], v[152:153], off offset:1024
	s_waitcnt vmcnt(7)
	v_mfma_f32_32x32x16_bf16 v[0:15], v[40:43], v[192:195], v[0:15]
	global_load_dwordx4 v[192:195], v[152:153], off offset:2048
	s_waitcnt vmcnt(7)
	v_mfma_f32_32x32x16_bf16 v[0:15], v[44:47], v[196:199], v[0:15]
	global_load_dwordx4 v[196:199], v[152:153], off offset:3072
	s_nop 11
	ds_write2_b32 v124, v0, v1 offset1:1
	ds_write2_b32 v124, v2, v3 offset0:2 offset1:3
	ds_write2_b32 v124, v4, v5 offset0:8 offset1:9
	ds_write2_b32 v124, v6, v7 offset0:10 offset1:11
	ds_write2_b32 v124, v8, v9 offset0:16 offset1:17
	ds_write2_b32 v124, v10, v11 offset0:18 offset1:19
	ds_write2_b32 v124, v12, v13 offset0:24 offset1:25
	ds_write2_b32 v124, v14, v15 offset0:26 offset1:27
	v_add_u32_e32 v124, 0x4080, v124
	s_waitcnt vmcnt(15)
	v_mfma_f32_32x32x16_bf16 v[0:15], v[16:19], v[200:203], 0
	global_load_dwordx4 v[200:203], v[154:155], off
	s_waitcnt vmcnt(15)
	v_mfma_f32_32x32x16_bf16 v[0:15], v[20:23], v[204:207], v[0:15]
	global_load_dwordx4 v[204:207], v[154:155], off offset:1024
	s_waitcnt vmcnt(15)
	v_mfma_f32_32x32x16_bf16 v[0:15], v[24:27], v[208:211], v[0:15]
	global_load_dwordx4 v[208:211], v[154:155], off offset:2048
	s_waitcnt vmcnt(15)
	v_mfma_f32_32x32x16_bf16 v[0:15], v[28:31], v[212:215], v[0:15]
	global_load_dwordx4 v[212:215], v[154:155], off offset:3072
	s_waitcnt vmcnt(15)
	v_mfma_f32_32x32x16_bf16 v[0:15], v[32:35], v[216:219], v[0:15]
	global_load_dwordx4 v[216:219], v[156:157], off
	s_waitcnt vmcnt(15)
	v_mfma_f32_32x32x16_bf16 v[0:15], v[36:39], v[220:223], v[0:15]
	global_load_dwordx4 v[220:223], v[156:157], off offset:1024
	s_waitcnt vmcnt(15)
	v_mfma_f32_32x32x16_bf16 v[0:15], v[40:43], v[224:227], v[0:15]
	global_load_dwordx4 v[224:227], v[156:157], off offset:2048
	s_waitcnt vmcnt(15)
	v_mfma_f32_32x32x16_bf16 v[0:15], v[44:47], v[228:231], v[0:15]
	global_load_dwordx4 v[228:231], v[156:157], off offset:3072
	s_nop 11
	ds_write2_b32 v124, v0, v1 offset1:1
	ds_write2_b32 v124, v2, v3 offset0:2 offset1:3
	ds_write2_b32 v124, v4, v5 offset0:8 offset1:9
	ds_write2_b32 v124, v6, v7 offset0:10 offset1:11
	ds_write2_b32 v124, v8, v9 offset0:16 offset1:17
	ds_write2_b32 v124, v10, v11 offset0:18 offset1:19
	ds_write2_b32 v124, v12, v13 offset0:24 offset1:25
	ds_write2_b32 v124, v14, v15 offset0:26 offset1:27
	v_add_u32_e32 v124, 0x4080, v124
	s_waitcnt vmcnt(15)
	v_mfma_f32_32x32x16_bf16 v[0:15], v[16:19], v[168:171], 0
	s_waitcnt vmcnt(14)
	v_mfma_f32_32x32x16_bf16 v[0:15], v[20:23], v[172:175], v[0:15]
	s_waitcnt vmcnt(13)
	v_mfma_f32_32x32x16_bf16 v[0:15], v[24:27], v[176:179], v[0:15]
	s_waitcnt vmcnt(12)
	v_mfma_f32_32x32x16_bf16 v[0:15], v[28:31], v[180:183], v[0:15]
	s_waitcnt vmcnt(11)
	v_mfma_f32_32x32x16_bf16 v[0:15], v[32:35], v[184:187], v[0:15]
	s_waitcnt vmcnt(10)
	v_mfma_f32_32x32x16_bf16 v[0:15], v[36:39], v[188:191], v[0:15]
	s_waitcnt vmcnt(9)
	v_mfma_f32_32x32x16_bf16 v[0:15], v[40:43], v[192:195], v[0:15]
	s_waitcnt vmcnt(8)
	v_mfma_f32_32x32x16_bf16 v[0:15], v[44:47], v[196:199], v[0:15]
	s_nop 11
	ds_write2_b32 v124, v0, v1 offset1:1
	ds_write2_b32 v124, v2, v3 offset0:2 offset1:3
	ds_write2_b32 v124, v4, v5 offset0:8 offset1:9
	ds_write2_b32 v124, v6, v7 offset0:10 offset1:11
	ds_write2_b32 v124, v8, v9 offset0:16 offset1:17
	ds_write2_b32 v124, v10, v11 offset0:18 offset1:19
	ds_write2_b32 v124, v12, v13 offset0:24 offset1:25
	ds_write2_b32 v124, v14, v15 offset0:26 offset1:27
	v_add_u32_e32 v124, 0x4080, v124
	s_waitcnt vmcnt(7)
	v_mfma_f32_32x32x16_bf16 v[0:15], v[16:19], v[200:203], 0
	s_waitcnt vmcnt(6)
	v_mfma_f32_32x32x16_bf16 v[0:15], v[20:23], v[204:207], v[0:15]
	s_waitcnt vmcnt(5)
	v_mfma_f32_32x32x16_bf16 v[0:15], v[24:27], v[208:211], v[0:15]
	s_waitcnt vmcnt(4)
	v_mfma_f32_32x32x16_bf16 v[0:15], v[28:31], v[212:215], v[0:15]
	s_waitcnt vmcnt(3)
	v_mfma_f32_32x32x16_bf16 v[0:15], v[32:35], v[216:219], v[0:15]
	s_waitcnt vmcnt(2)
	v_mfma_f32_32x32x16_bf16 v[0:15], v[36:39], v[220:223], v[0:15]
	s_waitcnt vmcnt(1)
	v_mfma_f32_32x32x16_bf16 v[0:15], v[40:43], v[224:227], v[0:15]
	s_waitcnt vmcnt(0)
; #define MFMA(a, b, c) __builtin_amdgcn_mfma_f32_32x32x16_bf16((a), (b), (c), 0, 0, 0)
; DI int crow(int i, int h) { return (i & 3) + 8 * (i >> 2) + 4 * h; }
; DI f32x16 zero16() { f32x16 z; for (int i = 0; i < 16; ++i) z[i] = 0.f; return z; }
; DI void peer_topk_item(const Params& p, int tt128, int head, char* smem) {
;     ...
;     for (int tt = 0; tt < 4; ++tt) {
;       f32x16 acc = zero16();
;       const u16* brow = pq + (((((size_t)(tok0 >> 5) + tt) * 8 + head) * 2 + half) * 8) * 512 + lane * 8;
; #pragma unroll
;       for (int ks = 0; ks < 8; ++ks) acc = MFMA(af[ks], ldg8(brow + ks * 512), acc);
; #pragma unroll
;       for (int i = 0; i < 16; ++i) sc[(half * 128 + tt * 32 + lr) * 129 + kt * 32 + crow(i, lh)] = acc[i];
;     }
;   }
;   __syncthreads();
;   if (tid < 256) {
;     float* row = sc + tid * 129;
;     float gm[8]; int gi[8];
; #pragma unroll
;     for (int g = 0; g < 8; ++g) {
;       float m = -INFINITY; int mi = g * 16;
; #pragma unroll
;       for (int j = 0; j < 16; ++j) { float v = row[g * 16 + j]; if (v > m) { m = v; mi = g * 16 + j; } }
;       gm[g] = m; gi[g] = mi;
;     }
	v_mfma_f32_32x32x16_bf16 v[0:15], v[44:47], v[228:231], v[0:15]
	s_nop 11
	ds_write2_b32 v124, v0, v1 offset1:1
	ds_write2_b32 v124, v2, v3 offset0:2 offset1:3
	ds_write2_b32 v124, v4, v5 offset0:8 offset1:9
	ds_write2_b32 v124, v6, v7 offset0:10 offset1:11
	ds_write2_b32 v124, v8, v9 offset0:16 offset1:17
	ds_write2_b32 v124, v10, v11 offset0:18 offset1:19
	ds_write2_b32 v124, v12, v13 offset0:24 offset1:25
	ds_write2_b32 v124, v14, v15 offset0:26 offset1:27
	v_add_u32_e32 v124, 0x4080, v124
	s_add_i32 s12, s2, s78
	s_add_i32 s13, s3, s78
	s_cmpk_gt_i32 s12, 0x7ff
	s_cselect_b32 s12, s2, s12
	s_cselect_b32 s13, s3, s13
	s_and_b32 s0, s13, 7
	s_ashr_i32 s10, s12, 3
	s_lshl_b32 s4, s0, 14
	s_lshl_b32 s0, s10, 2
	s_ashr_i32 s1, s0, 31
	s_lshl_b64 s[0:1], s[0:1], 17
	s_or_b32 s0, s0, s4
	v_lshl_add_u64 v[142:143], v[50:51], 0, s[0:1]
	s_mov_b32 s4, 0x16800000
	s_mov_b32 s5, 0
	s_mov_b64 s[8:9], 0x20000
	v_lshl_add_u64 v[142:143], v[142:143], 0, s[4:5]
	s_movk_i32 s10, 0x1000
	s_mov_b32 s11, 0
	v_lshl_add_u64 v[144:145], v[142:143], 0, s[10:11]
	v_lshl_add_u64 v[146:147], v[142:143], 0, s[8:9]
	v_lshl_add_u64 v[148:149], v[144:145], 0, s[8:9]
	global_load_dwordx4 v[168:171], v[142:143], off
	global_load_dwordx4 v[172:175], v[142:143], off offset:1024
	global_load_dwordx4 v[176:179], v[142:143], off offset:2048
	global_load_dwordx4 v[180:183], v[142:143], off offset:3072
	global_load_dwordx4 v[184:187], v[144:145], off
	global_load_dwordx4 v[188:191], v[144:145], off offset:1024
	global_load_dwordx4 v[192:195], v[144:145], off offset:2048
	global_load_dwordx4 v[196:199], v[144:145], off offset:3072
	global_load_dwordx4 v[200:203], v[146:147], off
	global_load_dwordx4 v[204:207], v[146:147], off offset:1024
	global_load_dwordx4 v[208:211], v[146:147], off offset:2048
	global_load_dwordx4 v[212:215], v[146:147], off offset:3072
	global_load_dwordx4 v[216:219], v[148:149], off
	global_load_dwordx4 v[220:223], v[148:149], off offset:1024
	global_load_dwordx4 v[224:227], v[148:149], off offset:2048
	global_load_dwordx4 v[228:231], v[148:149], off offset:3072
	s_mov_b64 s[0:1], 0x80000
	s_waitcnt lgkmcnt(0)
	s_barrier
	s_mov_b64 s[52:53], exec
	v_readlane_b32 s0, v255, 45
	v_readlane_b32 s1, v255, 46
	s_and_b64 s[0:1], s[52:53], s[0:1]
	s_mov_b64 exec, s[0:1]
	s_cbranch_execz .LBB0_968
	ds_read2_b32 v[16:17], v54 offset0:0 offset1:1
	ds_read2_b32 v[18:19], v54 offset0:2 offset1:3
	ds_read2_b32 v[20:21], v54 offset0:4 offset1:5
	ds_read2_b32 v[22:23], v54 offset0:6 offset1:7
	ds_read2_b32 v[24:25], v54 offset0:8 offset1:9
	ds_read2_b32 v[26:27], v54 offset0:10 offset1:11
	ds_read2_b32 v[28:29], v54 offset0:12 offset1:13
	ds_read2_b32 v[30:31], v54 offset0:14 offset1:15
	ds_read2_b32 v[124:125], v54 offset0:16 offset1:17
	ds_read2_b32 v[126:127], v54 offset0:18 offset1:19
	ds_read2_b32 v[128:129], v54 offset0:20 offset1:21
	ds_read2_b32 v[130:131], v54 offset0:22 offset1:23
	ds_read2_b32 v[132:133], v54 offset0:24 offset1:25
	ds_read2_b32 v[134:135], v54 offset0:26 offset1:27
	ds_read2_b32 v[136:137], v54 offset0:28 offset1:29
	ds_read2_b32 v[138:139], v54 offset0:30 offset1:31
	s_waitcnt lgkmcnt(8)
	v_cmp_gt_f32_e64 s[8:9], v17, v16
	v_cmp_gt_f32_e64 s[10:11], v19, v18
	v_cmp_gt_f32_e64 s[12:13], v21, v20
	v_cmp_gt_f32_e64 s[24:25], v23, v22
	v_cmp_gt_f32_e64 s[26:27], v25, v24
	v_cmp_gt_f32_e64 s[28:29], v27, v26
	v_cmp_gt_f32_e64 s[30:31], v29, v28
	v_cmp_gt_f32_e64 s[34:35], v31, v30
	v_cndmask_b32_e64 v16, v16, v17, s[8:9]
	v_cndmask_b32_e64 v32, 0, 1, s[8:9]
	v_cndmask_b32_e64 v18, v18, v19, s[10:11]
	v_cndmask_b32_e64 v33, 2, 3, s[10:11]
	v_cndmask_b32_e64 v20, v20, v21, s[12:13]
	v_cndmask_b32_e64 v34, 4, 5, s[12:13]
	v_cndmask_b32_e64 v22, v22, v23, s[24:25]
	v_cndmask_b32_e64 v35, 6, 7, s[24:25]
	v_cndmask_b32_e64 v24, v24, v25, s[26:27]
	v_cndmask_b32_e64 v36, 8, 9, s[26:27]
	v_cndmask_b32_e64 v26, v26, v27, s[28:29]
	v_cndmask_b32_e64 v37, 10, 11, s[28:29]
	v_cndmask_b32_e64 v28, v28, v29, s[30:31]
	v_cndmask_b32_e64 v38, 12, 13, s[30:31]
	v_cndmask_b32_e64 v30, v30, v31, s[34:35]
	v_cndmask_b32_e64 v39, 14, 15, s[34:35]
	v_cmp_gt_f32_e64 s[8:9], v18, v16
	v_cmp_gt_f32_e64 s[10:11], v22, v20
	v_cmp_gt_f32_e64 s[12:13], v26, v24
	v_cmp_gt_f32_e64 s[24:25], v30, v28
	v_cndmask_b32_e64 v16, v16, v18, s[8:9]
	v_cndmask_b32_e64 v32, v32, v33, s[8:9]
	v_cndmask_b32_e64 v20, v20, v22, s[10:11]
	v_cndmask_b32_e64 v34, v34, v35, s[10:11]
	v_cndmask_b32_e64 v24, v24, v26, s[12:13]
	v_cndmask_b32_e64 v36, v36, v37, s[12:13]
	v_cndmask_b32_e64 v28, v28, v30, s[24:25]
	v_cndmask_b32_e64 v38, v38, v39, s[24:25]
	v_cmp_gt_f32_e64 s[8:9], v20, v16
	v_cmp_gt_f32_e64 s[10:11], v28, v24
	s_nop 0
	v_cndmask_b32_e64 v16, v16, v20, s[8:9]
	v_cndmask_b32_e64 v32, v32, v34, s[8:9]
	v_cndmask_b32_e64 v24, v24, v28, s[10:11]
	v_cndmask_b32_e64 v36, v36, v38, s[10:11]
	v_cmp_gt_f32_e64 s[8:9], v24, v16
	s_nop 1
	v_cndmask_b32_e64 v16, v16, v24, s[8:9]
	v_cndmask_b32_e64 v32, v32, v36, s[8:9]
	v_mov_b32_e32 v0, v16
	v_mov_b32_e32 v8, v32
	ds_read2_b32 v[16:17], v54 offset0:32 offset1:33
	ds_read2_b32 v[18:19], v54 offset0:34 offset1:35
	ds_read2_b32 v[20:21], v54 offset0:36 offset1:37
	ds_read2_b32 v[22:23], v54 offset0:38 offset1:39
	ds_read2_b32 v[24:25], v54 offset0:40 offset1:41
	ds_read2_b32 v[26:27], v54 offset0:42 offset1:43
	ds_read2_b32 v[28:29], v54 offset0:44 offset1:45
	ds_read2_b32 v[30:31], v54 offset0:46 offset1:47
	s_waitcnt lgkmcnt(8)
; DI void peer_topk_item(const Params& p, int tt128, int head, char* smem) {
;     ...
; #pragma unroll
;     for (int g = 0; g < 8; ++g) {
;       float m = -INFINITY; int mi = g * 16;
; #pragma unroll
;       for (int j = 0; j < 16; ++j) { float v = row[g * 16 + j]; if (v > m) { m = v; mi = g * 16 + j; } }
;       gm[g] = m; gi[g] = mi;
;     }
	v_cmp_gt_f32_e64 s[8:9], v125, v124
	v_cmp_gt_f32_e64 s[10:11], v127, v126
	v_cmp_gt_f32_e64 s[12:13], v129, v128
	v_cmp_gt_f32_e64 s[24:25], v131, v130
	v_cmp_gt_f32_e64 s[26:27], v133, v132
	v_cmp_gt_f32_e64 s[28:29], v135, v134
	v_cmp_gt_f32_e64 s[30:31], v137, v136
	v_cmp_gt_f32_e64 s[34:35], v139, v138
	v_cndmask_b32_e64 v124, v124, v125, s[8:9]
	v_cndmask_b32_e64 v32, 0, 1, s[8:9]
	v_cndmask_b32_e64 v126, v126, v127, s[10:11]
	v_cndmask_b32_e64 v33, 2, 3, s[10:11]
	v_cndmask_b32_e64 v128, v128, v129, s[12:13]
	v_cndmask_b32_e64 v34, 4, 5, s[12:13]
	v_cndmask_b32_e64 v130, v130, v131, s[24:25]
	v_cndmask_b32_e64 v35, 6, 7, s[24:25]
	v_cndmask_b32_e64 v132, v132, v133, s[26:27]
	v_cndmask_b32_e64 v36, 8, 9, s[26:27]
	v_cndmask_b32_e64 v134, v134, v135, s[28:29]
	v_cndmask_b32_e64 v37, 10, 11, s[28:29]
	v_cndmask_b32_e64 v136, v136, v137, s[30:31]
	v_cndmask_b32_e64 v38, 12, 13, s[30:31]
	v_cndmask_b32_e64 v138, v138, v139, s[34:35]
	v_cndmask_b32_e64 v39, 14, 15, s[34:35]
	v_cmp_gt_f32_e64 s[8:9], v126, v124
	v_cmp_gt_f32_e64 s[10:11], v130, v128
	v_cmp_gt_f32_e64 s[12:13], v134, v132
	v_cmp_gt_f32_e64 s[24:25], v138, v136
	v_cndmask_b32_e64 v124, v124, v126, s[8:9]
	v_cndmask_b32_e64 v32, v32, v33, s[8:9]
	v_cndmask_b32_e64 v128, v128, v130, s[10:11]
	v_cndmask_b32_e64 v34, v34, v35, s[10:11]
	v_cndmask_b32_e64 v132, v132, v134, s[12:13]
	v_cndmask_b32_e64 v36, v36, v37, s[12:13]
	v_cndmask_b32_e64 v136, v136, v138, s[24:25]
	v_cndmask_b32_e64 v38, v38, v39, s[24:25]
	v_cmp_gt_f32_e64 s[8:9], v128, v124
	v_cmp_gt_f32_e64 s[10:11], v136, v132
	s_nop 0
	v_cndmask_b32_e64 v124, v124, v128, s[8:9]
	v_cndmask_b32_e64 v32, v32, v34, s[8:9]
	v_cndmask_b32_e64 v132, v132, v136, s[10:11]
	v_cndmask_b32_e64 v36, v36, v38, s[10:11]
	v_cmp_gt_f32_e64 s[8:9], v132, v124
	s_nop 1
	v_cndmask_b32_e64 v124, v124, v132, s[8:9]
	v_cndmask_b32_e64 v32, v32, v36, s[8:9]
	v_mov_b32_e32 v1, v124
	v_add_u32_e32 v9, 16, v32
	ds_read2_b32 v[124:125], v54 offset0:48 offset1:49
	ds_read2_b32 v[126:127], v54 offset0:50 offset1:51
	ds_read2_b32 v[128:129], v54 offset0:52 offset1:53
	ds_read2_b32 v[130:131], v54 offset0:54 offset1:55
	ds_read2_b32 v[132:133], v54 offset0:56 offset1:57
	ds_read2_b32 v[134:135], v54 offset0:58 offset1:59
	ds_read2_b32 v[136:137], v54 offset0:60 offset1:61
	ds_read2_b32 v[138:139], v54 offset0:62 offset1:63
	s_waitcnt lgkmcnt(8)
	v_cmp_gt_f32_e64 s[8:9], v17, v16
	v_cmp_gt_f32_e64 s[10:11], v19, v18
	v_cmp_gt_f32_e64 s[12:13], v21, v20
	v_cmp_gt_f32_e64 s[24:25], v23, v22
	v_cmp_gt_f32_e64 s[26:27], v25, v24
	v_cmp_gt_f32_e64 s[28:29], v27, v26
	v_cmp_gt_f32_e64 s[30:31], v29, v28
	v_cmp_gt_f32_e64 s[34:35], v31, v30
	v_cndmask_b32_e64 v16, v16, v17, s[8:9]
	v_cndmask_b32_e64 v32, 0, 1, s[8:9]
	v_cndmask_b32_e64 v18, v18, v19, s[10:11]
	v_cndmask_b32_e64 v33, 2, 3, s[10:11]
	v_cndmask_b32_e64 v20, v20, v21, s[12:13]
	v_cndmask_b32_e64 v34, 4, 5, s[12:13]
	v_cndmask_b32_e64 v22, v22, v23, s[24:25]
	v_cndmask_b32_e64 v35, 6, 7, s[24:25]
	v_cndmask_b32_e64 v24, v24, v25, s[26:27]
	v_cndmask_b32_e64 v36, 8, 9, s[26:27]
	v_cndmask_b32_e64 v26, v26, v27, s[28:29]
	v_cndmask_b32_e64 v37, 10, 11, s[28:29]
	v_cndmask_b32_e64 v28, v28, v29, s[30:31]
	v_cndmask_b32_e64 v38, 12, 13, s[30:31]
	v_cndmask_b32_e64 v30, v30, v31, s[34:35]
	v_cndmask_b32_e64 v39, 14, 15, s[34:35]
	v_cmp_gt_f32_e64 s[8:9], v18, v16
	v_cmp_gt_f32_e64 s[10:11], v22, v20
	v_cmp_gt_f32_e64 s[12:13], v26, v24
	v_cmp_gt_f32_e64 s[24:25], v30, v28
	v_cndmask_b32_e64 v16, v16, v18, s[8:9]
	v_cndmask_b32_e64 v32, v32, v33, s[8:9]
	v_cndmask_b32_e64 v20, v20, v22, s[10:11]
	v_cndmask_b32_e64 v34, v34, v35, s[10:11]
	v_cndmask_b32_e64 v24, v24, v26, s[12:13]
	v_cndmask_b32_e64 v36, v36, v37, s[12:13]
	v_cndmask_b32_e64 v28, v28, v30, s[24:25]
	v_cndmask_b32_e64 v38, v38, v39, s[24:25]
	v_cmp_gt_f32_e64 s[8:9], v20, v16
	v_cmp_gt_f32_e64 s[10:11], v28, v24
	s_nop 0
	v_cndmask_b32_e64 v16, v16, v20, s[8:9]
	v_cndmask_b32_e64 v32, v32, v34, s[8:9]
	v_cndmask_b32_e64 v24, v24, v28, s[10:11]
	v_cndmask_b32_e64 v36, v36, v38, s[10:11]
	v_cmp_gt_f32_e64 s[8:9], v24, v16
	s_nop 1
	v_cndmask_b32_e64 v16, v16, v24, s[8:9]
	v_cndmask_b32_e64 v32, v32, v36, s[8:9]
	v_mov_b32_e32 v2, v16
	v_add_u32_e32 v10, 32, v32
	ds_read2_b32 v[16:17], v54 offset0:64 offset1:65
	ds_read2_b32 v[18:19], v54 offset0:66 offset1:67
	ds_read2_b32 v[20:21], v54 offset0:68 offset1:69
	ds_read2_b32 v[22:23], v54 offset0:70 offset1:71
	ds_read2_b32 v[24:25], v54 offset0:72 offset1:73
	ds_read2_b32 v[26:27], v54 offset0:74 offset1:75
	ds_read2_b32 v[28:29], v54 offset0:76 offset1:77
	ds_read2_b32 v[30:31], v54 offset0:78 offset1:79
	s_waitcnt lgkmcnt(8)
; DI void peer_topk_item(const Params& p, int tt128, int head, char* smem) {
;     ...
; #pragma unroll
;     for (int g = 0; g < 8; ++g) {
;       float m = -INFINITY; int mi = g * 16;
; #pragma unroll
;       for (int j = 0; j < 16; ++j) { float v = row[g * 16 + j]; if (v > m) { m = v; mi = g * 16 + j; } }
;       gm[g] = m; gi[g] = mi;
;     }
	v_cmp_gt_f32_e64 s[8:9], v125, v124
	v_cmp_gt_f32_e64 s[10:11], v127, v126
	v_cmp_gt_f32_e64 s[12:13], v129, v128
	v_cmp_gt_f32_e64 s[24:25], v131, v130
	v_cmp_gt_f32_e64 s[26:27], v133, v132
	v_cmp_gt_f32_e64 s[28:29], v135, v134
	v_cmp_gt_f32_e64 s[30:31], v137, v136
	v_cmp_gt_f32_e64 s[34:35], v139, v138
	v_cndmask_b32_e64 v124, v124, v125, s[8:9]
	v_cndmask_b32_e64 v32, 0, 1, s[8:9]
	v_cndmask_b32_e64 v126, v126, v127, s[10:11]
	v_cndmask_b32_e64 v33, 2, 3, s[10:11]
	v_cndmask_b32_e64 v128, v128, v129, s[12:13]
	v_cndmask_b32_e64 v34, 4, 5, s[12:13]
	v_cndmask_b32_e64 v130, v130, v131, s[24:25]
	v_cndmask_b32_e64 v35, 6, 7, s[24:25]
	v_cndmask_b32_e64 v132, v132, v133, s[26:27]
	v_cndmask_b32_e64 v36, 8, 9, s[26:27]
	v_cndmask_b32_e64 v134, v134, v135, s[28:29]
	v_cndmask_b32_e64 v37, 10, 11, s[28:29]
	v_cndmask_b32_e64 v136, v136, v137, s[30:31]
	v_cndmask_b32_e64 v38, 12, 13, s[30:31]
	v_cndmask_b32_e64 v138, v138, v139, s[34:35]
	v_cndmask_b32_e64 v39, 14, 15, s[34:35]
	v_cmp_gt_f32_e64 s[8:9], v126, v124
	v_cmp_gt_f32_e64 s[10:11], v130, v128
	v_cmp_gt_f32_e64 s[12:13], v134, v132
	v_cmp_gt_f32_e64 s[24:25], v138, v136
	v_cndmask_b32_e64 v124, v124, v126, s[8:9]
	v_cndmask_b32_e64 v32, v32, v33, s[8:9]
	v_cndmask_b32_e64 v128, v128, v130, s[10:11]
	v_cndmask_b32_e64 v34, v34, v35, s[10:11]
	v_cndmask_b32_e64 v132, v132, v134, s[12:13]
	v_cndmask_b32_e64 v36, v36, v37, s[12:13]
	v_cndmask_b32_e64 v136, v136, v138, s[24:25]
	v_cndmask_b32_e64 v38, v38, v39, s[24:25]
	v_cmp_gt_f32_e64 s[8:9], v128, v124
	v_cmp_gt_f32_e64 s[10:11], v136, v132
	s_nop 0
	v_cndmask_b32_e64 v124, v124, v128, s[8:9]
	v_cndmask_b32_e64 v32, v32, v34, s[8:9]
	v_cndmask_b32_e64 v132, v132, v136, s[10:11]
	v_cndmask_b32_e64 v36, v36, v38, s[10:11]
	v_cmp_gt_f32_e64 s[8:9], v132, v124
	s_nop 1
	v_cndmask_b32_e64 v124, v124, v132, s[8:9]
	v_cndmask_b32_e64 v32, v32, v36, s[8:9]
	v_mov_b32_e32 v3, v124
	v_add_u32_e32 v11, 48, v32
	ds_read2_b32 v[124:125], v54 offset0:80 offset1:81
	ds_read2_b32 v[126:127], v54 offset0:82 offset1:83
	ds_read2_b32 v[128:129], v54 offset0:84 offset1:85
	ds_read2_b32 v[130:131], v54 offset0:86 offset1:87
	ds_read2_b32 v[132:133], v54 offset0:88 offset1:89
	ds_read2_b32 v[134:135], v54 offset0:90 offset1:91
	ds_read2_b32 v[136:137], v54 offset0:92 offset1:93
	ds_read2_b32 v[138:139], v54 offset0:94 offset1:95
	s_waitcnt lgkmcnt(8)
	v_cmp_gt_f32_e64 s[8:9], v17, v16
	v_cmp_gt_f32_e64 s[10:11], v19, v18
	v_cmp_gt_f32_e64 s[12:13], v21, v20
	v_cmp_gt_f32_e64 s[24:25], v23, v22
	v_cmp_gt_f32_e64 s[26:27], v25, v24
	v_cmp_gt_f32_e64 s[28:29], v27, v26
	v_cmp_gt_f32_e64 s[30:31], v29, v28
	v_cmp_gt_f32_e64 s[34:35], v31, v30
	v_cndmask_b32_e64 v16, v16, v17, s[8:9]
	v_cndmask_b32_e64 v32, 0, 1, s[8:9]
	v_cndmask_b32_e64 v18, v18, v19, s[10:11]
	v_cndmask_b32_e64 v33, 2, 3, s[10:11]
	v_cndmask_b32_e64 v20, v20, v21, s[12:13]
	v_cndmask_b32_e64 v34, 4, 5, s[12:13]
	v_cndmask_b32_e64 v22, v22, v23, s[24:25]
	v_cndmask_b32_e64 v35, 6, 7, s[24:25]
	v_cndmask_b32_e64 v24, v24, v25, s[26:27]
	v_cndmask_b32_e64 v36, 8, 9, s[26:27]
	v_cndmask_b32_e64 v26, v26, v27, s[28:29]
	v_cndmask_b32_e64 v37, 10, 11, s[28:29]
	v_cndmask_b32_e64 v28, v28, v29, s[30:31]
	v_cndmask_b32_e64 v38, 12, 13, s[30:31]
	v_cndmask_b32_e64 v30, v30, v31, s[34:35]
	v_cndmask_b32_e64 v39, 14, 15, s[34:35]
	v_cmp_gt_f32_e64 s[8:9], v18, v16
	v_cmp_gt_f32_e64 s[10:11], v22, v20
	v_cmp_gt_f32_e64 s[12:13], v26, v24
	v_cmp_gt_f32_e64 s[24:25], v30, v28
	v_cndmask_b32_e64 v16, v16, v18, s[8:9]
	v_cndmask_b32_e64 v32, v32, v33, s[8:9]
	v_cndmask_b32_e64 v20, v20, v22, s[10:11]
	v_cndmask_b32_e64 v34, v34, v35, s[10:11]
	v_cndmask_b32_e64 v24, v24, v26, s[12:13]
	v_cndmask_b32_e64 v36, v36, v37, s[12:13]
	v_cndmask_b32_e64 v28, v28, v30, s[24:25]
	v_cndmask_b32_e64 v38, v38, v39, s[24:25]
	v_cmp_gt_f32_e64 s[8:9], v20, v16
	v_cmp_gt_f32_e64 s[10:11], v28, v24
	s_nop 0
	v_cndmask_b32_e64 v16, v16, v20, s[8:9]
	v_cndmask_b32_e64 v32, v32, v34, s[8:9]
	v_cndmask_b32_e64 v24, v24, v28, s[10:11]
	v_cndmask_b32_e64 v36, v36, v38, s[10:11]
	v_cmp_gt_f32_e64 s[8:9], v24, v16
	s_nop 1
	v_cndmask_b32_e64 v16, v16, v24, s[8:9]
	v_cndmask_b32_e64 v32, v32, v36, s[8:9]
	v_mov_b32_e32 v4, v16
	v_add_u32_e32 v12, 64, v32
	ds_read2_b32 v[16:17], v54 offset0:96 offset1:97
	ds_read2_b32 v[18:19], v54 offset0:98 offset1:99
	ds_read2_b32 v[20:21], v54 offset0:100 offset1:101
	ds_read2_b32 v[22:23], v54 offset0:102 offset1:103
	ds_read2_b32 v[24:25], v54 offset0:104 offset1:105
	ds_read2_b32 v[26:27], v54 offset0:106 offset1:107
	ds_read2_b32 v[28:29], v54 offset0:108 offset1:109
	ds_read2_b32 v[30:31], v54 offset0:110 offset1:111
	s_waitcnt lgkmcnt(8)
; DI void peer_topk_item(const Params& p, int tt128, int head, char* smem) {
;     ...
; #pragma unroll
;     for (int g = 0; g < 8; ++g) {
;       float m = -INFINITY; int mi = g * 16;
; #pragma unroll
;       for (int j = 0; j < 16; ++j) { float v = row[g * 16 + j]; if (v > m) { m = v; mi = g * 16 + j; } }
;       gm[g] = m; gi[g] = mi;
;     }
	v_cmp_gt_f32_e64 s[8:9], v125, v124
	v_cmp_gt_f32_e64 s[10:11], v127, v126
	v_cmp_gt_f32_e64 s[12:13], v129, v128
	v_cmp_gt_f32_e64 s[24:25], v131, v130
	v_cmp_gt_f32_e64 s[26:27], v133, v132
	v_cmp_gt_f32_e64 s[28:29], v135, v134
	v_cmp_gt_f32_e64 s[30:31], v137, v136
	v_cmp_gt_f32_e64 s[34:35], v139, v138
	v_cndmask_b32_e64 v124, v124, v125, s[8:9]
	v_cndmask_b32_e64 v32, 0, 1, s[8:9]
	v_cndmask_b32_e64 v126, v126, v127, s[10:11]
	v_cndmask_b32_e64 v33, 2, 3, s[10:11]
	v_cndmask_b32_e64 v128, v128, v129, s[12:13]
	v_cndmask_b32_e64 v34, 4, 5, s[12:13]
	v_cndmask_b32_e64 v130, v130, v131, s[24:25]
	v_cndmask_b32_e64 v35, 6, 7, s[24:25]
	v_cndmask_b32_e64 v132, v132, v133, s[26:27]
	v_cndmask_b32_e64 v36, 8, 9, s[26:27]
	v_cndmask_b32_e64 v134, v134, v135, s[28:29]
	v_cndmask_b32_e64 v37, 10, 11, s[28:29]
	v_cndmask_b32_e64 v136, v136, v137, s[30:31]
	v_cndmask_b32_e64 v38, 12, 13, s[30:31]
	v_cndmask_b32_e64 v138, v138, v139, s[34:35]
	v_cndmask_b32_e64 v39, 14, 15, s[34:35]
	v_cmp_gt_f32_e64 s[8:9], v126, v124
	v_cmp_gt_f32_e64 s[10:11], v130, v128
	v_cmp_gt_f32_e64 s[12:13], v134, v132
	v_cmp_gt_f32_e64 s[24:25], v138, v136
	v_cndmask_b32_e64 v124, v124, v126, s[8:9]
	v_cndmask_b32_e64 v32, v32, v33, s[8:9]
	v_cndmask_b32_e64 v128, v128, v130, s[10:11]
	v_cndmask_b32_e64 v34, v34, v35, s[10:11]
	v_cndmask_b32_e64 v132, v132, v134, s[12:13]
	v_cndmask_b32_e64 v36, v36, v37, s[12:13]
	v_cndmask_b32_e64 v136, v136, v138, s[24:25]
	v_cndmask_b32_e64 v38, v38, v39, s[24:25]
	v_cmp_gt_f32_e64 s[8:9], v128, v124
	v_cmp_gt_f32_e64 s[10:11], v136, v132
	s_nop 0
	v_cndmask_b32_e64 v124, v124, v128, s[8:9]
	v_cndmask_b32_e64 v32, v32, v34, s[8:9]
	v_cndmask_b32_e64 v132, v132, v136, s[10:11]
	v_cndmask_b32_e64 v36, v36, v38, s[10:11]
	v_cmp_gt_f32_e64 s[8:9], v132, v124
	s_nop 1
	v_cndmask_b32_e64 v124, v124, v132, s[8:9]
	v_cndmask_b32_e64 v32, v32, v36, s[8:9]
	v_mov_b32_e32 v5, v124
	v_add_u32_e32 v13, 0x50, v32
	ds_read2_b32 v[124:125], v54 offset0:112 offset1:113
	ds_read2_b32 v[126:127], v54 offset0:114 offset1:115
	ds_read2_b32 v[128:129], v54 offset0:116 offset1:117
	ds_read2_b32 v[130:131], v54 offset0:118 offset1:119
	ds_read2_b32 v[132:133], v54 offset0:120 offset1:121
	ds_read2_b32 v[134:135], v54 offset0:122 offset1:123
	ds_read2_b32 v[136:137], v54 offset0:124 offset1:125
	ds_read2_b32 v[138:139], v54 offset0:126 offset1:127
	s_waitcnt lgkmcnt(8)
	v_cmp_gt_f32_e64 s[8:9], v17, v16
	v_cmp_gt_f32_e64 s[10:11], v19, v18
	v_cmp_gt_f32_e64 s[12:13], v21, v20
	v_cmp_gt_f32_e64 s[24:25], v23, v22
	v_cmp_gt_f32_e64 s[26:27], v25, v24
	v_cmp_gt_f32_e64 s[28:29], v27, v26
	v_cmp_gt_f32_e64 s[30:31], v29, v28
	v_cmp_gt_f32_e64 s[34:35], v31, v30
	v_cndmask_b32_e64 v16, v16, v17, s[8:9]
	v_cndmask_b32_e64 v32, 0, 1, s[8:9]
	v_cndmask_b32_e64 v18, v18, v19, s[10:11]
	v_cndmask_b32_e64 v33, 2, 3, s[10:11]
	v_cndmask_b32_e64 v20, v20, v21, s[12:13]
	v_cndmask_b32_e64 v34, 4, 5, s[12:13]
	v_cndmask_b32_e64 v22, v22, v23, s[24:25]
	v_cndmask_b32_e64 v35, 6, 7, s[24:25]
	v_cndmask_b32_e64 v24, v24, v25, s[26:27]
	v_cndmask_b32_e64 v36, 8, 9, s[26:27]
	v_cndmask_b32_e64 v26, v26, v27, s[28:29]
	v_cndmask_b32_e64 v37, 10, 11, s[28:29]
	v_cndmask_b32_e64 v28, v28, v29, s[30:31]
	v_cndmask_b32_e64 v38, 12, 13, s[30:31]
	v_cndmask_b32_e64 v30, v30, v31, s[34:35]
	v_cndmask_b32_e64 v39, 14, 15, s[34:35]
	v_cmp_gt_f32_e64 s[8:9], v18, v16
	v_cmp_gt_f32_e64 s[10:11], v22, v20
	v_cmp_gt_f32_e64 s[12:13], v26, v24
	v_cmp_gt_f32_e64 s[24:25], v30, v28
	v_cndmask_b32_e64 v16, v16, v18, s[8:9]
	v_cndmask_b32_e64 v32, v32, v33, s[8:9]
	v_cndmask_b32_e64 v20, v20, v22, s[10:11]
	v_cndmask_b32_e64 v34, v34, v35, s[10:11]
	v_cndmask_b32_e64 v24, v24, v26, s[12:13]
	v_cndmask_b32_e64 v36, v36, v37, s[12:13]
	v_cndmask_b32_e64 v28, v28, v30, s[24:25]
	v_cndmask_b32_e64 v38, v38, v39, s[24:25]
	v_cmp_gt_f32_e64 s[8:9], v20, v16
	v_cmp_gt_f32_e64 s[10:11], v28, v24
	s_nop 0
	v_cndmask_b32_e64 v16, v16, v20, s[8:9]
	v_cndmask_b32_e64 v32, v32, v34, s[8:9]
	v_cndmask_b32_e64 v24, v24, v28, s[10:11]
	v_cndmask_b32_e64 v36, v36, v38, s[10:11]
	v_cmp_gt_f32_e64 s[8:9], v24, v16
	s_nop 1
	v_cndmask_b32_e64 v16, v16, v24, s[8:9]
	v_cndmask_b32_e64 v32, v32, v36, s[8:9]
	v_mov_b32_e32 v6, v16
	v_add_u32_e32 v14, 0x60, v32
	s_waitcnt lgkmcnt(0)
; DI void peer_topk_item(const Params& p, int tt128, int head, char* smem) {
;     ...
; #pragma unroll
;     for (int g = 0; g < 8; ++g) {
;       float m = -INFINITY; int mi = g * 16;
; #pragma unroll
;       for (int j = 0; j < 16; ++j) { float v = row[g * 16 + j]; if (v > m) { m = v; mi = g * 16 + j; } }
;       gm[g] = m; gi[g] = mi;
;     }
; #pragma unroll 1
;     for (int r = 0; r < 16; ++r) {
;       float best = gm[0]; int bg = 0; int bi = gi[0];
; #pragma unroll
;       for (int g = 1; g < 8; ++g) if (gm[g] > best) { best = gm[g]; bg = g; bi = gi[g]; }
;       topv[tid * 16 + r] = best; topi[tid * 16 + r] = (unsigned char)bi;
;       row[bi] = -INFINITY;
;       float m = -INFINITY; int mi = bg * 16;
; #pragma unroll
;       for (int j = 0; j < 16; ++j) { float v = row[bg * 16 + j]; if (v > m) { m = v; mi = bg * 16 + j; } }
; #pragma unroll
;       for (int g = 0; g < 8; ++g) { gm[g] = (g == bg) ? m : gm[g]; gi[g] = (g == bg) ? mi : gi[g]; }
	v_cmp_gt_f32_e64 s[8:9], v125, v124
	v_cmp_gt_f32_e64 s[10:11], v127, v126
	v_cmp_gt_f32_e64 s[12:13], v129, v128
	v_cmp_gt_f32_e64 s[24:25], v131, v130
	v_cmp_gt_f32_e64 s[26:27], v133, v132
	v_cmp_gt_f32_e64 s[28:29], v135, v134
	v_cmp_gt_f32_e64 s[30:31], v137, v136
	v_cmp_gt_f32_e64 s[34:35], v139, v138
	v_cndmask_b32_e64 v124, v124, v125, s[8:9]
	v_cndmask_b32_e64 v32, 0, 1, s[8:9]
	v_cndmask_b32_e64 v126, v126, v127, s[10:11]
	v_cndmask_b32_e64 v33, 2, 3, s[10:11]
	v_cndmask_b32_e64 v128, v128, v129, s[12:13]
	v_cndmask_b32_e64 v34, 4, 5, s[12:13]
	v_cndmask_b32_e64 v130, v130, v131, s[24:25]
	v_cndmask_b32_e64 v35, 6, 7, s[24:25]
	v_cndmask_b32_e64 v132, v132, v133, s[26:27]
	v_cndmask_b32_e64 v36, 8, 9, s[26:27]
	v_cndmask_b32_e64 v134, v134, v135, s[28:29]
	v_cndmask_b32_e64 v37, 10, 11, s[28:29]
	v_cndmask_b32_e64 v136, v136, v137, s[30:31]
	v_cndmask_b32_e64 v38, 12, 13, s[30:31]
	v_cndmask_b32_e64 v138, v138, v139, s[34:35]
	v_cndmask_b32_e64 v39, 14, 15, s[34:35]
	v_cmp_gt_f32_e64 s[8:9], v126, v124
	v_cmp_gt_f32_e64 s[10:11], v130, v128
	v_cmp_gt_f32_e64 s[12:13], v134, v132
	v_cmp_gt_f32_e64 s[24:25], v138, v136
	v_cndmask_b32_e64 v124, v124, v126, s[8:9]
	v_cndmask_b32_e64 v32, v32, v33, s[8:9]
	v_cndmask_b32_e64 v128, v128, v130, s[10:11]
	v_cndmask_b32_e64 v34, v34, v35, s[10:11]
	v_cndmask_b32_e64 v132, v132, v134, s[12:13]
	v_cndmask_b32_e64 v36, v36, v37, s[12:13]
	v_cndmask_b32_e64 v136, v136, v138, s[24:25]
	v_cndmask_b32_e64 v38, v38, v39, s[24:25]
	v_cmp_gt_f32_e64 s[8:9], v128, v124
	v_cmp_gt_f32_e64 s[10:11], v136, v132
	s_nop 0
	v_cndmask_b32_e64 v124, v124, v128, s[8:9]
	v_cndmask_b32_e64 v32, v32, v34, s[8:9]
	v_cndmask_b32_e64 v132, v132, v136, s[10:11]
	v_cndmask_b32_e64 v36, v36, v38, s[10:11]
	v_cmp_gt_f32_e64 s[8:9], v132, v124
	s_nop 1
	v_cndmask_b32_e64 v124, v124, v132, s[8:9]
	v_cndmask_b32_e64 v32, v32, v36, s[8:9]
	v_mov_b32_e32 v7, v124
	v_add_u32_e32 v15, 0x70, v32
	v_cmp_gt_f32_e64 s[8:9], v1, v0
	v_cmp_gt_f32_e64 s[10:11], v3, v2
	v_cmp_gt_f32_e64 s[12:13], v5, v4
	v_cmp_gt_f32_e64 s[24:25], v7, v6
	v_cndmask_b32_e64 v40, v0, v1, s[8:9]
	v_cndmask_b32_e64 v44, 0, 1, s[8:9]
	v_cndmask_b32_e64 v141, v8, v9, s[8:9]
	v_cndmask_b32_e64 v41, v2, v3, s[10:11]
	v_cndmask_b32_e64 v45, 2, 3, s[10:11]
	v_cndmask_b32_e64 v142, v10, v11, s[10:11]
	v_cndmask_b32_e64 v42, v4, v5, s[12:13]
	v_cndmask_b32_e64 v46, 4, 5, s[12:13]
	v_cndmask_b32_e64 v143, v12, v13, s[12:13]
	v_cndmask_b32_e64 v43, v6, v7, s[24:25]
	v_cndmask_b32_e64 v47, 6, 7, s[24:25]
	v_cndmask_b32_e64 v144, v14, v15, s[24:25]
	v_cmp_gt_f32_e64 s[8:9], v41, v40
	v_cmp_gt_f32_e64 s[10:11], v43, v42
	s_nop 0
	v_cndmask_b32_e64 v40, v40, v41, s[8:9]
	v_cndmask_b32_e64 v44, v44, v45, s[8:9]
	v_cndmask_b32_e64 v141, v141, v142, s[8:9]
	v_cndmask_b32_e64 v42, v42, v43, s[10:11]
	v_cndmask_b32_e64 v46, v46, v47, s[10:11]
	v_cndmask_b32_e64 v143, v143, v144, s[10:11]
	v_cmp_gt_f32_e64 s[8:9], v42, v40
	s_nop 1
	v_cndmask_b32_e64 v40, v40, v42, s[8:9]
	v_cndmask_b32_e64 v44, v44, v46, s[8:9]
	v_cndmask_b32_e64 v141, v141, v143, s[8:9]
	ds_write_b32 v55, v40
	ds_write_b8 v57, v141
	v_lshl_add_u32 v146, v141, 2, v54
	ds_write_b32 v146, v60
	v_lshl_add_u32 v147, v44, 6, v54
	ds_read2_b32 v[16:17], v147 offset0:0 offset1:1
	ds_read2_b32 v[18:19], v147 offset0:2 offset1:3
	ds_read2_b32 v[20:21], v147 offset0:4 offset1:5
	ds_read2_b32 v[22:23], v147 offset0:6 offset1:7
	ds_read2_b32 v[24:25], v147 offset0:8 offset1:9
	ds_read2_b32 v[26:27], v147 offset0:10 offset1:11
	ds_read2_b32 v[28:29], v147 offset0:12 offset1:13
	ds_read2_b32 v[30:31], v147 offset0:14 offset1:15
	s_waitcnt lgkmcnt(0)
	v_cmp_gt_f32_e64 s[8:9], v17, v16
	v_cmp_gt_f32_e64 s[10:11], v19, v18
	v_cmp_gt_f32_e64 s[12:13], v21, v20
	v_cmp_gt_f32_e64 s[24:25], v23, v22
	v_cmp_gt_f32_e64 s[26:27], v25, v24
	v_cmp_gt_f32_e64 s[28:29], v27, v26
	v_cmp_gt_f32_e64 s[30:31], v29, v28
	v_cmp_gt_f32_e64 s[34:35], v31, v30
	v_cndmask_b32_e64 v16, v16, v17, s[8:9]
	v_cndmask_b32_e64 v32, 0, 1, s[8:9]
	v_cndmask_b32_e64 v18, v18, v19, s[10:11]
	v_cndmask_b32_e64 v33, 2, 3, s[10:11]
	v_cndmask_b32_e64 v20, v20, v21, s[12:13]
	v_cndmask_b32_e64 v34, 4, 5, s[12:13]
	v_cndmask_b32_e64 v22, v22, v23, s[24:25]
	v_cndmask_b32_e64 v35, 6, 7, s[24:25]
	v_cndmask_b32_e64 v24, v24, v25, s[26:27]
	v_cndmask_b32_e64 v36, 8, 9, s[26:27]
	v_cndmask_b32_e64 v26, v26, v27, s[28:29]
	v_cndmask_b32_e64 v37, 10, 11, s[28:29]
	v_cndmask_b32_e64 v28, v28, v29, s[30:31]
	v_cndmask_b32_e64 v38, 12, 13, s[30:31]
	v_cndmask_b32_e64 v30, v30, v31, s[34:35]
	v_cndmask_b32_e64 v39, 14, 15, s[34:35]
	v_cmp_gt_f32_e64 s[8:9], v18, v16
	v_cmp_gt_f32_e64 s[10:11], v22, v20
	v_cmp_gt_f32_e64 s[12:13], v26, v24
	v_cmp_gt_f32_e64 s[24:25], v30, v28
	v_cndmask_b32_e64 v16, v16, v18, s[8:9]
	v_cndmask_b32_e64 v32, v32, v33, s[8:9]
	v_cndmask_b32_e64 v20, v20, v22, s[10:11]
	v_cndmask_b32_e64 v34, v34, v35, s[10:11]
	v_cndmask_b32_e64 v24, v24, v26, s[12:13]
	v_cndmask_b32_e64 v36, v36, v37, s[12:13]
	v_cndmask_b32_e64 v28, v28, v30, s[24:25]
	v_cndmask_b32_e64 v38, v38, v39, s[24:25]
	v_cmp_gt_f32_e64 s[8:9], v20, v16
	v_cmp_gt_f32_e64 s[10:11], v28, v24
	s_nop 0
	v_cndmask_b32_e64 v16, v16, v20, s[8:9]
	v_cndmask_b32_e64 v32, v32, v34, s[8:9]
	v_cndmask_b32_e64 v24, v24, v28, s[10:11]
	v_cndmask_b32_e64 v36, v36, v38, s[10:11]
	v_cmp_gt_f32_e64 s[8:9], v24, v16
	s_nop 1
	v_cndmask_b32_e64 v16, v16, v24, s[8:9]
	v_cndmask_b32_e64 v32, v32, v36, s[8:9]
	v_lshl_add_u32 v148, v44, 4, v32
	v_cmp_eq_u32_e64 s[8:9], 0, v44
	v_cmp_eq_u32_e64 s[10:11], 1, v44
	v_cmp_eq_u32_e64 s[12:13], 2, v44
	v_cmp_eq_u32_e64 s[24:25], 3, v44
	v_cmp_eq_u32_e64 s[26:27], 4, v44
; DI void peer_topk_item(const Params& p, int tt128, int head, char* smem) {
;     ...
;     for (int r = 0; r < 16; ++r) {
;       float best = gm[0]; int bg = 0; int bi = gi[0];
; #pragma unroll
;       for (int g = 1; g < 8; ++g) if (gm[g] > best) { best = gm[g]; bg = g; bi = gi[g]; }
;       topv[tid * 16 + r] = best; topi[tid * 16 + r] = (unsigned char)bi;
;       row[bi] = -INFINITY;
;       float m = -INFINITY; int mi = bg * 16;
; #pragma unroll
;       for (int j = 0; j < 16; ++j) { float v = row[bg * 16 + j]; if (v > m) { m = v; mi = bg * 16 + j; } }
; #pragma unroll
;       for (int g = 0; g < 8; ++g) { gm[g] = (g == bg) ? m : gm[g]; gi[g] = (g == bg) ? mi : gi[g]; }
	v_cmp_eq_u32_e64 s[28:29], 5, v44
	v_cmp_eq_u32_e64 s[30:31], 6, v44
	v_cmp_eq_u32_e64 s[34:35], 7, v44
	v_cndmask_b32_e64 v0, v0, v16, s[8:9]
	v_cndmask_b32_e64 v8, v8, v148, s[8:9]
	v_cndmask_b32_e64 v1, v1, v16, s[10:11]
	v_cndmask_b32_e64 v9, v9, v148, s[10:11]
	v_cndmask_b32_e64 v2, v2, v16, s[12:13]
	v_cndmask_b32_e64 v10, v10, v148, s[12:13]
	v_cndmask_b32_e64 v3, v3, v16, s[24:25]
	v_cndmask_b32_e64 v11, v11, v148, s[24:25]
	v_cndmask_b32_e64 v4, v4, v16, s[26:27]
	v_cndmask_b32_e64 v12, v12, v148, s[26:27]
	v_cndmask_b32_e64 v5, v5, v16, s[28:29]
	v_cndmask_b32_e64 v13, v13, v148, s[28:29]
	v_cndmask_b32_e64 v6, v6, v16, s[30:31]
	v_cndmask_b32_e64 v14, v14, v148, s[30:31]
	v_cndmask_b32_e64 v7, v7, v16, s[34:35]
	v_cndmask_b32_e64 v15, v15, v148, s[34:35]
	v_cmp_gt_f32_e64 s[8:9], v1, v0
	v_cmp_gt_f32_e64 s[10:11], v3, v2
	v_cmp_gt_f32_e64 s[12:13], v5, v4
	v_cmp_gt_f32_e64 s[24:25], v7, v6
	v_cndmask_b32_e64 v40, v0, v1, s[8:9]
	v_cndmask_b32_e64 v44, 0, 1, s[8:9]
	v_cndmask_b32_e64 v141, v8, v9, s[8:9]
	v_cndmask_b32_e64 v41, v2, v3, s[10:11]
	v_cndmask_b32_e64 v45, 2, 3, s[10:11]
	v_cndmask_b32_e64 v142, v10, v11, s[10:11]
	v_cndmask_b32_e64 v42, v4, v5, s[12:13]
	v_cndmask_b32_e64 v46, 4, 5, s[12:13]
	v_cndmask_b32_e64 v143, v12, v13, s[12:13]
	v_cndmask_b32_e64 v43, v6, v7, s[24:25]
	v_cndmask_b32_e64 v47, 6, 7, s[24:25]
	v_cndmask_b32_e64 v144, v14, v15, s[24:25]
	v_cmp_gt_f32_e64 s[8:9], v41, v40
	v_cmp_gt_f32_e64 s[10:11], v43, v42
	s_nop 0
	v_cndmask_b32_e64 v40, v40, v41, s[8:9]
	v_cndmask_b32_e64 v44, v44, v45, s[8:9]
	v_cndmask_b32_e64 v141, v141, v142, s[8:9]
	v_cndmask_b32_e64 v42, v42, v43, s[10:11]
	v_cndmask_b32_e64 v46, v46, v47, s[10:11]
	v_cndmask_b32_e64 v143, v143, v144, s[10:11]
	v_cmp_gt_f32_e64 s[8:9], v42, v40
	s_nop 1
	v_cndmask_b32_e64 v40, v40, v42, s[8:9]
	v_cndmask_b32_e64 v44, v44, v46, s[8:9]
	v_cndmask_b32_e64 v141, v141, v143, s[8:9]
	ds_write_b32 v55, v40 offset:4
	ds_write_b8 v57, v141 offset:1
	v_lshl_add_u32 v146, v141, 2, v54
	ds_write_b32 v146, v60
	v_lshl_add_u32 v147, v44, 6, v54
	ds_read2_b32 v[16:17], v147 offset0:0 offset1:1
	ds_read2_b32 v[18:19], v147 offset0:2 offset1:3
	ds_read2_b32 v[20:21], v147 offset0:4 offset1:5
	ds_read2_b32 v[22:23], v147 offset0:6 offset1:7
	ds_read2_b32 v[24:25], v147 offset0:8 offset1:9
	ds_read2_b32 v[26:27], v147 offset0:10 offset1:11
	ds_read2_b32 v[28:29], v147 offset0:12 offset1:13
	ds_read2_b32 v[30:31], v147 offset0:14 offset1:15
	s_waitcnt lgkmcnt(0)
	v_cmp_gt_f32_e64 s[8:9], v17, v16
	v_cmp_gt_f32_e64 s[10:11], v19, v18
	v_cmp_gt_f32_e64 s[12:13], v21, v20
	v_cmp_gt_f32_e64 s[24:25], v23, v22
	v_cmp_gt_f32_e64 s[26:27], v25, v24
	v_cmp_gt_f32_e64 s[28:29], v27, v26
	v_cmp_gt_f32_e64 s[30:31], v29, v28
	v_cmp_gt_f32_e64 s[34:35], v31, v30
	v_cndmask_b32_e64 v16, v16, v17, s[8:9]
	v_cndmask_b32_e64 v32, 0, 1, s[8:9]
	v_cndmask_b32_e64 v18, v18, v19, s[10:11]
	v_cndmask_b32_e64 v33, 2, 3, s[10:11]
	v_cndmask_b32_e64 v20, v20, v21, s[12:13]
	v_cndmask_b32_e64 v34, 4, 5, s[12:13]
	v_cndmask_b32_e64 v22, v22, v23, s[24:25]
	v_cndmask_b32_e64 v35, 6, 7, s[24:25]
	v_cndmask_b32_e64 v24, v24, v25, s[26:27]
	v_cndmask_b32_e64 v36, 8, 9, s[26:27]
	v_cndmask_b32_e64 v26, v26, v27, s[28:29]
	v_cndmask_b32_e64 v37, 10, 11, s[28:29]
	v_cndmask_b32_e64 v28, v28, v29, s[30:31]
	v_cndmask_b32_e64 v38, 12, 13, s[30:31]
	v_cndmask_b32_e64 v30, v30, v31, s[34:35]
	v_cndmask_b32_e64 v39, 14, 15, s[34:35]
	v_cmp_gt_f32_e64 s[8:9], v18, v16
	v_cmp_gt_f32_e64 s[10:11], v22, v20
	v_cmp_gt_f32_e64 s[12:13], v26, v24
	v_cmp_gt_f32_e64 s[24:25], v30, v28
	v_cndmask_b32_e64 v16, v16, v18, s[8:9]
	v_cndmask_b32_e64 v32, v32, v33, s[8:9]
	v_cndmask_b32_e64 v20, v20, v22, s[10:11]
	v_cndmask_b32_e64 v34, v34, v35, s[10:11]
	v_cndmask_b32_e64 v24, v24, v26, s[12:13]
	v_cndmask_b32_e64 v36, v36, v37, s[12:13]
	v_cndmask_b32_e64 v28, v28, v30, s[24:25]
	v_cndmask_b32_e64 v38, v38, v39, s[24:25]
	v_cmp_gt_f32_e64 s[8:9], v20, v16
	v_cmp_gt_f32_e64 s[10:11], v28, v24
	s_nop 0
	v_cndmask_b32_e64 v16, v16, v20, s[8:9]
	v_cndmask_b32_e64 v32, v32, v34, s[8:9]
	v_cndmask_b32_e64 v24, v24, v28, s[10:11]
	v_cndmask_b32_e64 v36, v36, v38, s[10:11]
	v_cmp_gt_f32_e64 s[8:9], v24, v16
	s_nop 1
	v_cndmask_b32_e64 v16, v16, v24, s[8:9]
	v_cndmask_b32_e64 v32, v32, v36, s[8:9]
	v_lshl_add_u32 v148, v44, 4, v32
	v_cmp_eq_u32_e64 s[8:9], 0, v44
	v_cmp_eq_u32_e64 s[10:11], 1, v44
	v_cmp_eq_u32_e64 s[12:13], 2, v44
	v_cmp_eq_u32_e64 s[24:25], 3, v44
	v_cmp_eq_u32_e64 s[26:27], 4, v44
	v_cmp_eq_u32_e64 s[28:29], 5, v44
	v_cmp_eq_u32_e64 s[30:31], 6, v44
	v_cmp_eq_u32_e64 s[34:35], 7, v44
	v_cndmask_b32_e64 v0, v0, v16, s[8:9]
	v_cndmask_b32_e64 v8, v8, v148, s[8:9]
	v_cndmask_b32_e64 v1, v1, v16, s[10:11]
	v_cndmask_b32_e64 v9, v9, v148, s[10:11]
	v_cndmask_b32_e64 v2, v2, v16, s[12:13]
	v_cndmask_b32_e64 v10, v10, v148, s[12:13]
	v_cndmask_b32_e64 v3, v3, v16, s[24:25]
	v_cndmask_b32_e64 v11, v11, v148, s[24:25]
	v_cndmask_b32_e64 v4, v4, v16, s[26:27]
	v_cndmask_b32_e64 v12, v12, v148, s[26:27]
	v_cndmask_b32_e64 v5, v5, v16, s[28:29]
	v_cndmask_b32_e64 v13, v13, v148, s[28:29]
	v_cndmask_b32_e64 v6, v6, v16, s[30:31]
	v_cndmask_b32_e64 v14, v14, v148, s[30:31]
	v_cndmask_b32_e64 v7, v7, v16, s[34:35]
	v_cndmask_b32_e64 v15, v15, v148, s[34:35]
	v_cmp_gt_f32_e64 s[8:9], v1, v0
	v_cmp_gt_f32_e64 s[10:11], v3, v2
	v_cmp_gt_f32_e64 s[12:13], v5, v4
	v_cmp_gt_f32_e64 s[24:25], v7, v6
	v_cndmask_b32_e64 v40, v0, v1, s[8:9]
	v_cndmask_b32_e64 v44, 0, 1, s[8:9]
	v_cndmask_b32_e64 v141, v8, v9, s[8:9]
	v_cndmask_b32_e64 v41, v2, v3, s[10:11]
	v_cndmask_b32_e64 v45, 2, 3, s[10:11]
	v_cndmask_b32_e64 v142, v10, v11, s[10:11]
	v_cndmask_b32_e64 v42, v4, v5, s[12:13]
	v_cndmask_b32_e64 v46, 4, 5, s[12:13]
	v_cndmask_b32_e64 v143, v12, v13, s[12:13]
	v_cndmask_b32_e64 v43, v6, v7, s[24:25]
	v_cndmask_b32_e64 v47, 6, 7, s[24:25]
	v_cndmask_b32_e64 v144, v14, v15, s[24:25]
	v_cmp_gt_f32_e64 s[8:9], v41, v40
	v_cmp_gt_f32_e64 s[10:11], v43, v42
	s_nop 0
	v_cndmask_b32_e64 v40, v40, v41, s[8:9]
	v_cndmask_b32_e64 v44, v44, v45, s[8:9]
	v_cndmask_b32_e64 v141, v141, v142, s[8:9]
	v_cndmask_b32_e64 v42, v42, v43, s[10:11]
	v_cndmask_b32_e64 v46, v46, v47, s[10:11]
	v_cndmask_b32_e64 v143, v143, v144, s[10:11]
	v_cmp_gt_f32_e64 s[8:9], v42, v40
	s_nop 1
	v_cndmask_b32_e64 v40, v40, v42, s[8:9]
	v_cndmask_b32_e64 v44, v44, v46, s[8:9]
	v_cndmask_b32_e64 v141, v141, v143, s[8:9]
	ds_write_b32 v55, v40 offset:8
	ds_write_b8 v57, v141 offset:2
	v_lshl_add_u32 v146, v141, 2, v54
	ds_write_b32 v146, v60
	v_lshl_add_u32 v147, v44, 6, v54
	ds_read2_b32 v[16:17], v147 offset0:0 offset1:1
	ds_read2_b32 v[18:19], v147 offset0:2 offset1:3
	ds_read2_b32 v[20:21], v147 offset0:4 offset1:5
	ds_read2_b32 v[22:23], v147 offset0:6 offset1:7
	ds_read2_b32 v[24:25], v147 offset0:8 offset1:9
	ds_read2_b32 v[26:27], v147 offset0:10 offset1:11
	ds_read2_b32 v[28:29], v147 offset0:12 offset1:13
	ds_read2_b32 v[30:31], v147 offset0:14 offset1:15
	s_waitcnt lgkmcnt(0)
; DI void peer_topk_item(const Params& p, int tt128, int head, char* smem) {
;     ...
;     for (int r = 0; r < 16; ++r) {
;       float best = gm[0]; int bg = 0; int bi = gi[0];
; #pragma unroll
;       for (int g = 1; g < 8; ++g) if (gm[g] > best) { best = gm[g]; bg = g; bi = gi[g]; }
;       topv[tid * 16 + r] = best; topi[tid * 16 + r] = (unsigned char)bi;
;       row[bi] = -INFINITY;
;       float m = -INFINITY; int mi = bg * 16;
; #pragma unroll
;       for (int j = 0; j < 16; ++j) { float v = row[bg * 16 + j]; if (v > m) { m = v; mi = bg * 16 + j; } }
; #pragma unroll
;       for (int g = 0; g < 8; ++g) { gm[g] = (g == bg) ? m : gm[g]; gi[g] = (g == bg) ? mi : gi[g]; }
	v_cmp_gt_f32_e64 s[8:9], v17, v16
	v_cmp_gt_f32_e64 s[10:11], v19, v18
	v_cmp_gt_f32_e64 s[12:13], v21, v20
	v_cmp_gt_f32_e64 s[24:25], v23, v22
	v_cmp_gt_f32_e64 s[26:27], v25, v24
	v_cmp_gt_f32_e64 s[28:29], v27, v26
	v_cmp_gt_f32_e64 s[30:31], v29, v28
	v_cmp_gt_f32_e64 s[34:35], v31, v30
	v_cndmask_b32_e64 v16, v16, v17, s[8:9]
	v_cndmask_b32_e64 v32, 0, 1, s[8:9]
	v_cndmask_b32_e64 v18, v18, v19, s[10:11]
	v_cndmask_b32_e64 v33, 2, 3, s[10:11]
	v_cndmask_b32_e64 v20, v20, v21, s[12:13]
	v_cndmask_b32_e64 v34, 4, 5, s[12:13]
	v_cndmask_b32_e64 v22, v22, v23, s[24:25]
	v_cndmask_b32_e64 v35, 6, 7, s[24:25]
	v_cndmask_b32_e64 v24, v24, v25, s[26:27]
	v_cndmask_b32_e64 v36, 8, 9, s[26:27]
	v_cndmask_b32_e64 v26, v26, v27, s[28:29]
	v_cndmask_b32_e64 v37, 10, 11, s[28:29]
	v_cndmask_b32_e64 v28, v28, v29, s[30:31]
	v_cndmask_b32_e64 v38, 12, 13, s[30:31]
	v_cndmask_b32_e64 v30, v30, v31, s[34:35]
	v_cndmask_b32_e64 v39, 14, 15, s[34:35]
	v_cmp_gt_f32_e64 s[8:9], v18, v16
	v_cmp_gt_f32_e64 s[10:11], v22, v20
	v_cmp_gt_f32_e64 s[12:13], v26, v24
	v_cmp_gt_f32_e64 s[24:25], v30, v28
	v_cndmask_b32_e64 v16, v16, v18, s[8:9]
	v_cndmask_b32_e64 v32, v32, v33, s[8:9]
	v_cndmask_b32_e64 v20, v20, v22, s[10:11]
	v_cndmask_b32_e64 v34, v34, v35, s[10:11]
	v_cndmask_b32_e64 v24, v24, v26, s[12:13]
	v_cndmask_b32_e64 v36, v36, v37, s[12:13]
	v_cndmask_b32_e64 v28, v28, v30, s[24:25]
	v_cndmask_b32_e64 v38, v38, v39, s[24:25]
	v_cmp_gt_f32_e64 s[8:9], v20, v16
	v_cmp_gt_f32_e64 s[10:11], v28, v24
	s_nop 0
	v_cndmask_b32_e64 v16, v16, v20, s[8:9]
	v_cndmask_b32_e64 v32, v32, v34, s[8:9]
	v_cndmask_b32_e64 v24, v24, v28, s[10:11]
	v_cndmask_b32_e64 v36, v36, v38, s[10:11]
	v_cmp_gt_f32_e64 s[8:9], v24, v16
	s_nop 1
	v_cndmask_b32_e64 v16, v16, v24, s[8:9]
	v_cndmask_b32_e64 v32, v32, v36, s[8:9]
	v_lshl_add_u32 v148, v44, 4, v32
	v_cmp_eq_u32_e64 s[8:9], 0, v44
	v_cmp_eq_u32_e64 s[10:11], 1, v44
	v_cmp_eq_u32_e64 s[12:13], 2, v44
	v_cmp_eq_u32_e64 s[24:25], 3, v44
	v_cmp_eq_u32_e64 s[26:27], 4, v44
	v_cmp_eq_u32_e64 s[28:29], 5, v44
	v_cmp_eq_u32_e64 s[30:31], 6, v44
	v_cmp_eq_u32_e64 s[34:35], 7, v44
	v_cndmask_b32_e64 v0, v0, v16, s[8:9]
	v_cndmask_b32_e64 v8, v8, v148, s[8:9]
	v_cndmask_b32_e64 v1, v1, v16, s[10:11]
	v_cndmask_b32_e64 v9, v9, v148, s[10:11]
	v_cndmask_b32_e64 v2, v2, v16, s[12:13]
	v_cndmask_b32_e64 v10, v10, v148, s[12:13]
	v_cndmask_b32_e64 v3, v3, v16, s[24:25]
	v_cndmask_b32_e64 v11, v11, v148, s[24:25]
	v_cndmask_b32_e64 v4, v4, v16, s[26:27]
	v_cndmask_b32_e64 v12, v12, v148, s[26:27]
	v_cndmask_b32_e64 v5, v5, v16, s[28:29]
	v_cndmask_b32_e64 v13, v13, v148, s[28:29]
	v_cndmask_b32_e64 v6, v6, v16, s[30:31]
	v_cndmask_b32_e64 v14, v14, v148, s[30:31]
	v_cndmask_b32_e64 v7, v7, v16, s[34:35]
	v_cndmask_b32_e64 v15, v15, v148, s[34:35]
	v_cmp_gt_f32_e64 s[8:9], v1, v0
	v_cmp_gt_f32_e64 s[10:11], v3, v2
	v_cmp_gt_f32_e64 s[12:13], v5, v4
	v_cmp_gt_f32_e64 s[24:25], v7, v6
	v_cndmask_b32_e64 v40, v0, v1, s[8:9]
	v_cndmask_b32_e64 v44, 0, 1, s[8:9]
	v_cndmask_b32_e64 v141, v8, v9, s[8:9]
	v_cndmask_b32_e64 v41, v2, v3, s[10:11]
	v_cndmask_b32_e64 v45, 2, 3, s[10:11]
	v_cndmask_b32_e64 v142, v10, v11, s[10:11]
	v_cndmask_b32_e64 v42, v4, v5, s[12:13]
	v_cndmask_b32_e64 v46, 4, 5, s[12:13]
	v_cndmask_b32_e64 v143, v12, v13, s[12:13]
	v_cndmask_b32_e64 v43, v6, v7, s[24:25]
	v_cndmask_b32_e64 v47, 6, 7, s[24:25]
	v_cndmask_b32_e64 v144, v14, v15, s[24:25]
	v_cmp_gt_f32_e64 s[8:9], v41, v40
	v_cmp_gt_f32_e64 s[10:11], v43, v42
	s_nop 0
	v_cndmask_b32_e64 v40, v40, v41, s[8:9]
	v_cndmask_b32_e64 v44, v44, v45, s[8:9]
	v_cndmask_b32_e64 v141, v141, v142, s[8:9]
	v_cndmask_b32_e64 v42, v42, v43, s[10:11]
	v_cndmask_b32_e64 v46, v46, v47, s[10:11]
	v_cndmask_b32_e64 v143, v143, v144, s[10:11]
	v_cmp_gt_f32_e64 s[8:9], v42, v40
	s_nop 1
	v_cndmask_b32_e64 v40, v40, v42, s[8:9]
	v_cndmask_b32_e64 v44, v44, v46, s[8:9]
	v_cndmask_b32_e64 v141, v141, v143, s[8:9]
	ds_write_b32 v55, v40 offset:12
	ds_write_b8 v57, v141 offset:3
	v_lshl_add_u32 v146, v141, 2, v54
	ds_write_b32 v146, v60
	v_lshl_add_u32 v147, v44, 6, v54
	ds_read2_b32 v[16:17], v147 offset0:0 offset1:1
	ds_read2_b32 v[18:19], v147 offset0:2 offset1:3
	ds_read2_b32 v[20:21], v147 offset0:4 offset1:5
	ds_read2_b32 v[22:23], v147 offset0:6 offset1:7
	ds_read2_b32 v[24:25], v147 offset0:8 offset1:9
	ds_read2_b32 v[26:27], v147 offset0:10 offset1:11
	ds_read2_b32 v[28:29], v147 offset0:12 offset1:13
	ds_read2_b32 v[30:31], v147 offset0:14 offset1:15
	s_waitcnt lgkmcnt(0)
; DI void peer_topk_item(const Params& p, int tt128, int head, char* smem) {
;     ...
;     for (int r = 0; r < 16; ++r) {
;       float best = gm[0]; int bg = 0; int bi = gi[0];
; #pragma unroll
;       for (int g = 1; g < 8; ++g) if (gm[g] > best) { best = gm[g]; bg = g; bi = gi[g]; }
;       topv[tid * 16 + r] = best; topi[tid * 16 + r] = (unsigned char)bi;
;       row[bi] = -INFINITY;
;       float m = -INFINITY; int mi = bg * 16;
; #pragma unroll
;       for (int j = 0; j < 16; ++j) { float v = row[bg * 16 + j]; if (v > m) { m = v; mi = bg * 16 + j; } }
; #pragma unroll
;       for (int g = 0; g < 8; ++g) { gm[g] = (g == bg) ? m : gm[g]; gi[g] = (g == bg) ? mi : gi[g]; }
	v_cmp_gt_f32_e64 s[8:9], v17, v16
	v_cmp_gt_f32_e64 s[10:11], v19, v18
	v_cmp_gt_f32_e64 s[12:13], v21, v20
	v_cmp_gt_f32_e64 s[24:25], v23, v22
	v_cmp_gt_f32_e64 s[26:27], v25, v24
	v_cmp_gt_f32_e64 s[28:29], v27, v26
	v_cmp_gt_f32_e64 s[30:31], v29, v28
	v_cmp_gt_f32_e64 s[34:35], v31, v30
	v_cndmask_b32_e64 v16, v16, v17, s[8:9]
	v_cndmask_b32_e64 v32, 0, 1, s[8:9]
	v_cndmask_b32_e64 v18, v18, v19, s[10:11]
	v_cndmask_b32_e64 v33, 2, 3, s[10:11]
	v_cndmask_b32_e64 v20, v20, v21, s[12:13]
	v_cndmask_b32_e64 v34, 4, 5, s[12:13]
	v_cndmask_b32_e64 v22, v22, v23, s[24:25]
	v_cndmask_b32_e64 v35, 6, 7, s[24:25]
	v_cndmask_b32_e64 v24, v24, v25, s[26:27]
	v_cndmask_b32_e64 v36, 8, 9, s[26:27]
	v_cndmask_b32_e64 v26, v26, v27, s[28:29]
	v_cndmask_b32_e64 v37, 10, 11, s[28:29]
	v_cndmask_b32_e64 v28, v28, v29, s[30:31]
	v_cndmask_b32_e64 v38, 12, 13, s[30:31]
	v_cndmask_b32_e64 v30, v30, v31, s[34:35]
	v_cndmask_b32_e64 v39, 14, 15, s[34:35]
	v_cmp_gt_f32_e64 s[8:9], v18, v16
	v_cmp_gt_f32_e64 s[10:11], v22, v20
	v_cmp_gt_f32_e64 s[12:13], v26, v24
	v_cmp_gt_f32_e64 s[24:25], v30, v28
	v_cndmask_b32_e64 v16, v16, v18, s[8:9]
	v_cndmask_b32_e64 v32, v32, v33, s[8:9]
	v_cndmask_b32_e64 v20, v20, v22, s[10:11]
	v_cndmask_b32_e64 v34, v34, v35, s[10:11]
	v_cndmask_b32_e64 v24, v24, v26, s[12:13]
	v_cndmask_b32_e64 v36, v36, v37, s[12:13]
	v_cndmask_b32_e64 v28, v28, v30, s[24:25]
	v_cndmask_b32_e64 v38, v38, v39, s[24:25]
	v_cmp_gt_f32_e64 s[8:9], v20, v16
	v_cmp_gt_f32_e64 s[10:11], v28, v24
	s_nop 0
	v_cndmask_b32_e64 v16, v16, v20, s[8:9]
	v_cndmask_b32_e64 v32, v32, v34, s[8:9]
	v_cndmask_b32_e64 v24, v24, v28, s[10:11]
	v_cndmask_b32_e64 v36, v36, v38, s[10:11]
	v_cmp_gt_f32_e64 s[8:9], v24, v16
	s_nop 1
	v_cndmask_b32_e64 v16, v16, v24, s[8:9]
	v_cndmask_b32_e64 v32, v32, v36, s[8:9]
	v_lshl_add_u32 v148, v44, 4, v32
	v_cmp_eq_u32_e64 s[8:9], 0, v44
	v_cmp_eq_u32_e64 s[10:11], 1, v44
	v_cmp_eq_u32_e64 s[12:13], 2, v44
	v_cmp_eq_u32_e64 s[24:25], 3, v44
	v_cmp_eq_u32_e64 s[26:27], 4, v44
	v_cmp_eq_u32_e64 s[28:29], 5, v44
	v_cmp_eq_u32_e64 s[30:31], 6, v44
	v_cmp_eq_u32_e64 s[34:35], 7, v44
	v_cndmask_b32_e64 v0, v0, v16, s[8:9]
	v_cndmask_b32_e64 v8, v8, v148, s[8:9]
	v_cndmask_b32_e64 v1, v1, v16, s[10:11]
	v_cndmask_b32_e64 v9, v9, v148, s[10:11]
	v_cndmask_b32_e64 v2, v2, v16, s[12:13]
	v_cndmask_b32_e64 v10, v10, v148, s[12:13]
	v_cndmask_b32_e64 v3, v3, v16, s[24:25]
	v_cndmask_b32_e64 v11, v11, v148, s[24:25]
	v_cndmask_b32_e64 v4, v4, v16, s[26:27]
	v_cndmask_b32_e64 v12, v12, v148, s[26:27]
	v_cndmask_b32_e64 v5, v5, v16, s[28:29]
	v_cndmask_b32_e64 v13, v13, v148, s[28:29]
	v_cndmask_b32_e64 v6, v6, v16, s[30:31]
	v_cndmask_b32_e64 v14, v14, v148, s[30:31]
	v_cndmask_b32_e64 v7, v7, v16, s[34:35]
	v_cndmask_b32_e64 v15, v15, v148, s[34:35]
	v_cmp_gt_f32_e64 s[8:9], v1, v0
	v_cmp_gt_f32_e64 s[10:11], v3, v2
	v_cmp_gt_f32_e64 s[12:13], v5, v4
	v_cmp_gt_f32_e64 s[24:25], v7, v6
	v_cndmask_b32_e64 v40, v0, v1, s[8:9]
	v_cndmask_b32_e64 v44, 0, 1, s[8:9]
	v_cndmask_b32_e64 v141, v8, v9, s[8:9]
	v_cndmask_b32_e64 v41, v2, v3, s[10:11]
	v_cndmask_b32_e64 v45, 2, 3, s[10:11]
	v_cndmask_b32_e64 v142, v10, v11, s[10:11]
	v_cndmask_b32_e64 v42, v4, v5, s[12:13]
	v_cndmask_b32_e64 v46, 4, 5, s[12:13]
	v_cndmask_b32_e64 v143, v12, v13, s[12:13]
	v_cndmask_b32_e64 v43, v6, v7, s[24:25]
	v_cndmask_b32_e64 v47, 6, 7, s[24:25]
	v_cndmask_b32_e64 v144, v14, v15, s[24:25]
	v_cmp_gt_f32_e64 s[8:9], v41, v40
	v_cmp_gt_f32_e64 s[10:11], v43, v42
	s_nop 0
	v_cndmask_b32_e64 v40, v40, v41, s[8:9]
	v_cndmask_b32_e64 v44, v44, v45, s[8:9]
	v_cndmask_b32_e64 v141, v141, v142, s[8:9]
	v_cndmask_b32_e64 v42, v42, v43, s[10:11]
	v_cndmask_b32_e64 v46, v46, v47, s[10:11]
	v_cndmask_b32_e64 v143, v143, v144, s[10:11]
	v_cmp_gt_f32_e64 s[8:9], v42, v40
	s_nop 1
	v_cndmask_b32_e64 v40, v40, v42, s[8:9]
	v_cndmask_b32_e64 v44, v44, v46, s[8:9]
	v_cndmask_b32_e64 v141, v141, v143, s[8:9]
	ds_write_b32 v55, v40 offset:16
	ds_write_b8 v57, v141 offset:4
	v_lshl_add_u32 v146, v141, 2, v54
	ds_write_b32 v146, v60
	v_lshl_add_u32 v147, v44, 6, v54
	ds_read2_b32 v[16:17], v147 offset0:0 offset1:1
	ds_read2_b32 v[18:19], v147 offset0:2 offset1:3
	ds_read2_b32 v[20:21], v147 offset0:4 offset1:5
	ds_read2_b32 v[22:23], v147 offset0:6 offset1:7
	ds_read2_b32 v[24:25], v147 offset0:8 offset1:9
	ds_read2_b32 v[26:27], v147 offset0:10 offset1:11
	ds_read2_b32 v[28:29], v147 offset0:12 offset1:13
	ds_read2_b32 v[30:31], v147 offset0:14 offset1:15
	s_waitcnt lgkmcnt(0)
; DI void peer_topk_item(const Params& p, int tt128, int head, char* smem) {
;     ...
;     for (int r = 0; r < 16; ++r) {
;       float best = gm[0]; int bg = 0; int bi = gi[0];
; #pragma unroll
;       for (int g = 1; g < 8; ++g) if (gm[g] > best) { best = gm[g]; bg = g; bi = gi[g]; }
;       topv[tid * 16 + r] = best; topi[tid * 16 + r] = (unsigned char)bi;
;       row[bi] = -INFINITY;
;       float m = -INFINITY; int mi = bg * 16;
; #pragma unroll
;       for (int j = 0; j < 16; ++j) { float v = row[bg * 16 + j]; if (v > m) { m = v; mi = bg * 16 + j; } }
; #pragma unroll
;       for (int g = 0; g < 8; ++g) { gm[g] = (g == bg) ? m : gm[g]; gi[g] = (g == bg) ? mi : gi[g]; }
	v_cmp_gt_f32_e64 s[8:9], v17, v16
	v_cmp_gt_f32_e64 s[10:11], v19, v18
	v_cmp_gt_f32_e64 s[12:13], v21, v20
	v_cmp_gt_f32_e64 s[24:25], v23, v22
	v_cmp_gt_f32_e64 s[26:27], v25, v24
	v_cmp_gt_f32_e64 s[28:29], v27, v26
	v_cmp_gt_f32_e64 s[30:31], v29, v28
	v_cmp_gt_f32_e64 s[34:35], v31, v30
	v_cndmask_b32_e64 v16, v16, v17, s[8:9]
	v_cndmask_b32_e64 v32, 0, 1, s[8:9]
	v_cndmask_b32_e64 v18, v18, v19, s[10:11]
	v_cndmask_b32_e64 v33, 2, 3, s[10:11]
	v_cndmask_b32_e64 v20, v20, v21, s[12:13]
	v_cndmask_b32_e64 v34, 4, 5, s[12:13]
	v_cndmask_b32_e64 v22, v22, v23, s[24:25]
	v_cndmask_b32_e64 v35, 6, 7, s[24:25]
	v_cndmask_b32_e64 v24, v24, v25, s[26:27]
	v_cndmask_b32_e64 v36, 8, 9, s[26:27]
	v_cndmask_b32_e64 v26, v26, v27, s[28:29]
	v_cndmask_b32_e64 v37, 10, 11, s[28:29]
	v_cndmask_b32_e64 v28, v28, v29, s[30:31]
	v_cndmask_b32_e64 v38, 12, 13, s[30:31]
	v_cndmask_b32_e64 v30, v30, v31, s[34:35]
	v_cndmask_b32_e64 v39, 14, 15, s[34:35]
	v_cmp_gt_f32_e64 s[8:9], v18, v16
	v_cmp_gt_f32_e64 s[10:11], v22, v20
	v_cmp_gt_f32_e64 s[12:13], v26, v24
	v_cmp_gt_f32_e64 s[24:25], v30, v28
	v_cndmask_b32_e64 v16, v16, v18, s[8:9]
	v_cndmask_b32_e64 v32, v32, v33, s[8:9]
	v_cndmask_b32_e64 v20, v20, v22, s[10:11]
	v_cndmask_b32_e64 v34, v34, v35, s[10:11]
	v_cndmask_b32_e64 v24, v24, v26, s[12:13]
	v_cndmask_b32_e64 v36, v36, v37, s[12:13]
	v_cndmask_b32_e64 v28, v28, v30, s[24:25]
	v_cndmask_b32_e64 v38, v38, v39, s[24:25]
	v_cmp_gt_f32_e64 s[8:9], v20, v16
	v_cmp_gt_f32_e64 s[10:11], v28, v24
	s_nop 0
	v_cndmask_b32_e64 v16, v16, v20, s[8:9]
	v_cndmask_b32_e64 v32, v32, v34, s[8:9]
	v_cndmask_b32_e64 v24, v24, v28, s[10:11]
	v_cndmask_b32_e64 v36, v36, v38, s[10:11]
	v_cmp_gt_f32_e64 s[8:9], v24, v16
	s_nop 1
	v_cndmask_b32_e64 v16, v16, v24, s[8:9]
	v_cndmask_b32_e64 v32, v32, v36, s[8:9]
	v_lshl_add_u32 v148, v44, 4, v32
	v_cmp_eq_u32_e64 s[8:9], 0, v44
	v_cmp_eq_u32_e64 s[10:11], 1, v44
	v_cmp_eq_u32_e64 s[12:13], 2, v44
	v_cmp_eq_u32_e64 s[24:25], 3, v44
	v_cmp_eq_u32_e64 s[26:27], 4, v44
	v_cmp_eq_u32_e64 s[28:29], 5, v44
	v_cmp_eq_u32_e64 s[30:31], 6, v44
	v_cmp_eq_u32_e64 s[34:35], 7, v44
	v_cndmask_b32_e64 v0, v0, v16, s[8:9]
	v_cndmask_b32_e64 v8, v8, v148, s[8:9]
	v_cndmask_b32_e64 v1, v1, v16, s[10:11]
	v_cndmask_b32_e64 v9, v9, v148, s[10:11]
	v_cndmask_b32_e64 v2, v2, v16, s[12:13]
	v_cndmask_b32_e64 v10, v10, v148, s[12:13]
	v_cndmask_b32_e64 v3, v3, v16, s[24:25]
	v_cndmask_b32_e64 v11, v11, v148, s[24:25]
	v_cndmask_b32_e64 v4, v4, v16, s[26:27]
	v_cndmask_b32_e64 v12, v12, v148, s[26:27]
	v_cndmask_b32_e64 v5, v5, v16, s[28:29]
	v_cndmask_b32_e64 v13, v13, v148, s[28:29]
	v_cndmask_b32_e64 v6, v6, v16, s[30:31]
	v_cndmask_b32_e64 v14, v14, v148, s[30:31]
	v_cndmask_b32_e64 v7, v7, v16, s[34:35]
	v_cndmask_b32_e64 v15, v15, v148, s[34:35]
	v_cmp_gt_f32_e64 s[8:9], v1, v0
	v_cmp_gt_f32_e64 s[10:11], v3, v2
	v_cmp_gt_f32_e64 s[12:13], v5, v4
	v_cmp_gt_f32_e64 s[24:25], v7, v6
	v_cndmask_b32_e64 v40, v0, v1, s[8:9]
	v_cndmask_b32_e64 v44, 0, 1, s[8:9]
	v_cndmask_b32_e64 v141, v8, v9, s[8:9]
	v_cndmask_b32_e64 v41, v2, v3, s[10:11]
	v_cndmask_b32_e64 v45, 2, 3, s[10:11]
	v_cndmask_b32_e64 v142, v10, v11, s[10:11]
	v_cndmask_b32_e64 v42, v4, v5, s[12:13]
	v_cndmask_b32_e64 v46, 4, 5, s[12:13]
	v_cndmask_b32_e64 v143, v12, v13, s[12:13]
	v_cndmask_b32_e64 v43, v6, v7, s[24:25]
	v_cndmask_b32_e64 v47, 6, 7, s[24:25]
	v_cndmask_b32_e64 v144, v14, v15, s[24:25]
	v_cmp_gt_f32_e64 s[8:9], v41, v40
	v_cmp_gt_f32_e64 s[10:11], v43, v42
	s_nop 0
	v_cndmask_b32_e64 v40, v40, v41, s[8:9]
	v_cndmask_b32_e64 v44, v44, v45, s[8:9]
	v_cndmask_b32_e64 v141, v141, v142, s[8:9]
	v_cndmask_b32_e64 v42, v42, v43, s[10:11]
	v_cndmask_b32_e64 v46, v46, v47, s[10:11]
	v_cndmask_b32_e64 v143, v143, v144, s[10:11]
	v_cmp_gt_f32_e64 s[8:9], v42, v40
	s_nop 1
	v_cndmask_b32_e64 v40, v40, v42, s[8:9]
	v_cndmask_b32_e64 v44, v44, v46, s[8:9]
	v_cndmask_b32_e64 v141, v141, v143, s[8:9]
	ds_write_b32 v55, v40 offset:20
	ds_write_b8 v57, v141 offset:5
	v_lshl_add_u32 v146, v141, 2, v54
	ds_write_b32 v146, v60
	v_lshl_add_u32 v147, v44, 6, v54
	ds_read2_b32 v[16:17], v147 offset0:0 offset1:1
	ds_read2_b32 v[18:19], v147 offset0:2 offset1:3
	ds_read2_b32 v[20:21], v147 offset0:4 offset1:5
	ds_read2_b32 v[22:23], v147 offset0:6 offset1:7
	ds_read2_b32 v[24:25], v147 offset0:8 offset1:9
	ds_read2_b32 v[26:27], v147 offset0:10 offset1:11
	ds_read2_b32 v[28:29], v147 offset0:12 offset1:13
	ds_read2_b32 v[30:31], v147 offset0:14 offset1:15
	s_waitcnt lgkmcnt(0)
; DI void peer_topk_item(const Params& p, int tt128, int head, char* smem) {
;     ...
; #pragma unroll 1
;     for (int r = 0; r < 16; ++r) {
;       float best = gm[0]; int bg = 0; int bi = gi[0];
; #pragma unroll
;       for (int g = 1; g < 8; ++g) if (gm[g] > best) { best = gm[g]; bg = g; bi = gi[g]; }
;       topv[tid * 16 + r] = best; topi[tid * 16 + r] = (unsigned char)bi;
;       row[bi] = -INFINITY;
;       float m = -INFINITY; int mi = bg * 16;
; #pragma unroll
;       for (int j = 0; j < 16; ++j) { float v = row[bg * 16 + j]; if (v > m) { m = v; mi = bg * 16 + j; } }
; #pragma unroll
;       for (int g = 0; g < 8; ++g) { gm[g] = (g == bg) ? m : gm[g]; gi[g] = (g == bg) ? mi : gi[g]; }
;     }
	v_cmp_gt_f32_e64 s[8:9], v17, v16
	v_cmp_gt_f32_e64 s[10:11], v19, v18
	v_cmp_gt_f32_e64 s[12:13], v21, v20
	v_cmp_gt_f32_e64 s[24:25], v23, v22
	v_cmp_gt_f32_e64 s[26:27], v25, v24
	v_cmp_gt_f32_e64 s[28:29], v27, v26
	v_cmp_gt_f32_e64 s[30:31], v29, v28
	v_cmp_gt_f32_e64 s[34:35], v31, v30
	v_cndmask_b32_e64 v16, v16, v17, s[8:9]
	v_cndmask_b32_e64 v32, 0, 1, s[8:9]
	v_cndmask_b32_e64 v18, v18, v19, s[10:11]
	v_cndmask_b32_e64 v33, 2, 3, s[10:11]
	v_cndmask_b32_e64 v20, v20, v21, s[12:13]
	v_cndmask_b32_e64 v34, 4, 5, s[12:13]
	v_cndmask_b32_e64 v22, v22, v23, s[24:25]
	v_cndmask_b32_e64 v35, 6, 7, s[24:25]
	v_cndmask_b32_e64 v24, v24, v25, s[26:27]
	v_cndmask_b32_e64 v36, 8, 9, s[26:27]
	v_cndmask_b32_e64 v26, v26, v27, s[28:29]
	v_cndmask_b32_e64 v37, 10, 11, s[28:29]
	v_cndmask_b32_e64 v28, v28, v29, s[30:31]
	v_cndmask_b32_e64 v38, 12, 13, s[30:31]
	v_cndmask_b32_e64 v30, v30, v31, s[34:35]
	v_cndmask_b32_e64 v39, 14, 15, s[34:35]
	v_cmp_gt_f32_e64 s[8:9], v18, v16
	v_cmp_gt_f32_e64 s[10:11], v22, v20
	v_cmp_gt_f32_e64 s[12:13], v26, v24
	v_cmp_gt_f32_e64 s[24:25], v30, v28
	v_cndmask_b32_e64 v16, v16, v18, s[8:9]
	v_cndmask_b32_e64 v32, v32, v33, s[8:9]
	v_cndmask_b32_e64 v20, v20, v22, s[10:11]
	v_cndmask_b32_e64 v34, v34, v35, s[10:11]
	v_cndmask_b32_e64 v24, v24, v26, s[12:13]
	v_cndmask_b32_e64 v36, v36, v37, s[12:13]
	v_cndmask_b32_e64 v28, v28, v30, s[24:25]
	v_cndmask_b32_e64 v38, v38, v39, s[24:25]
	v_cmp_gt_f32_e64 s[8:9], v20, v16
	v_cmp_gt_f32_e64 s[10:11], v28, v24
	s_nop 0
	v_cndmask_b32_e64 v16, v16, v20, s[8:9]
	v_cndmask_b32_e64 v32, v32, v34, s[8:9]
	v_cndmask_b32_e64 v24, v24, v28, s[10:11]
	v_cndmask_b32_e64 v36, v36, v38, s[10:11]
	v_cmp_gt_f32_e64 s[8:9], v24, v16
	s_nop 1
	v_cndmask_b32_e64 v16, v16, v24, s[8:9]
	v_cndmask_b32_e64 v32, v32, v36, s[8:9]
	v_lshl_add_u32 v148, v44, 4, v32
	v_cmp_eq_u32_e64 s[8:9], 0, v44
	v_cmp_eq_u32_e64 s[10:11], 1, v44
	v_cmp_eq_u32_e64 s[12:13], 2, v44
	v_cmp_eq_u32_e64 s[24:25], 3, v44
	v_cmp_eq_u32_e64 s[26:27], 4, v44
	v_cmp_eq_u32_e64 s[28:29], 5, v44
	v_cmp_eq_u32_e64 s[30:31], 6, v44
	v_cmp_eq_u32_e64 s[34:35], 7, v44
	v_cndmask_b32_e64 v0, v0, v16, s[8:9]
	v_cndmask_b32_e64 v8, v8, v148, s[8:9]
	v_cndmask_b32_e64 v1, v1, v16, s[10:11]
	v_cndmask_b32_e64 v9, v9, v148, s[10:11]
	v_cndmask_b32_e64 v2, v2, v16, s[12:13]
	v_cndmask_b32_e64 v10, v10, v148, s[12:13]
	v_cndmask_b32_e64 v3, v3, v16, s[24:25]
	v_cndmask_b32_e64 v11, v11, v148, s[24:25]
	v_cndmask_b32_e64 v4, v4, v16, s[26:27]
	v_cndmask_b32_e64 v12, v12, v148, s[26:27]
	v_cndmask_b32_e64 v5, v5, v16, s[28:29]
	v_cndmask_b32_e64 v13, v13, v148, s[28:29]
	v_cndmask_b32_e64 v6, v6, v16, s[30:31]
	v_cndmask_b32_e64 v14, v14, v148, s[30:31]
	v_cndmask_b32_e64 v7, v7, v16, s[34:35]
	v_cndmask_b32_e64 v15, v15, v148, s[34:35]
	v_cmp_gt_f32_e64 s[8:9], v1, v0
	v_cmp_gt_f32_e64 s[10:11], v3, v2
	v_cmp_gt_f32_e64 s[12:13], v5, v4
	v_cmp_gt_f32_e64 s[24:25], v7, v6
	v_cndmask_b32_e64 v40, v0, v1, s[8:9]
	v_cndmask_b32_e64 v44, 0, 1, s[8:9]
	v_cndmask_b32_e64 v141, v8, v9, s[8:9]
	v_cndmask_b32_e64 v41, v2, v3, s[10:11]
	v_cndmask_b32_e64 v45, 2, 3, s[10:11]
	v_cndmask_b32_e64 v142, v10, v11, s[10:11]
	v_cndmask_b32_e64 v42, v4, v5, s[12:13]
	v_cndmask_b32_e64 v46, 4, 5, s[12:13]
	v_cndmask_b32_e64 v143, v12, v13, s[12:13]
	v_cndmask_b32_e64 v43, v6, v7, s[24:25]
	v_cndmask_b32_e64 v47, 6, 7, s[24:25]
	v_cndmask_b32_e64 v144, v14, v15, s[24:25]
	v_cmp_gt_f32_e64 s[8:9], v41, v40
	v_cmp_gt_f32_e64 s[10:11], v43, v42
	s_nop 0
	v_cndmask_b32_e64 v40, v40, v41, s[8:9]
	v_cndmask_b32_e64 v44, v44, v45, s[8:9]
	v_cndmask_b32_e64 v141, v141, v142, s[8:9]
	v_cndmask_b32_e64 v42, v42, v43, s[10:11]
	v_cndmask_b32_e64 v46, v46, v47, s[10:11]
	v_cndmask_b32_e64 v143, v143, v144, s[10:11]
	v_cmp_gt_f32_e64 s[8:9], v42, v40
	s_nop 1
	v_cndmask_b32_e64 v40, v40, v42, s[8:9]
	v_cndmask_b32_e64 v44, v44, v46, s[8:9]
	v_cndmask_b32_e64 v141, v141, v143, s[8:9]
	ds_write_b32 v55, v40 offset:24
	ds_write_b8 v57, v141 offset:6
	v_lshl_add_u32 v146, v141, 2, v54
	ds_write_b32 v146, v60
	v_lshl_add_u32 v147, v44, 6, v54
	ds_read2_b32 v[16:17], v147 offset0:0 offset1:1
	ds_read2_b32 v[18:19], v147 offset0:2 offset1:3
	ds_read2_b32 v[20:21], v147 offset0:4 offset1:5
	ds_read2_b32 v[22:23], v147 offset0:6 offset1:7
	ds_read2_b32 v[24:25], v147 offset0:8 offset1:9
	ds_read2_b32 v[26:27], v147 offset0:10 offset1:11
	ds_read2_b32 v[28:29], v147 offset0:12 offset1:13
	ds_read2_b32 v[30:31], v147 offset0:14 offset1:15
	s_waitcnt lgkmcnt(0)
; DI void peer_topk_item(const Params& p, int tt128, int head, char* smem) {
;     ...
; #pragma unroll 1
;     for (int r = 0; r < 16; ++r) {
;       float best = gm[0]; int bg = 0; int bi = gi[0];
; #pragma unroll
;       for (int g = 1; g < 8; ++g) if (gm[g] > best) { best = gm[g]; bg = g; bi = gi[g]; }
;       topv[tid * 16 + r] = best; topi[tid * 16 + r] = (unsigned char)bi;
;       row[bi] = -INFINITY;
;       float m = -INFINITY; int mi = bg * 16;
; #pragma unroll
;       for (int j = 0; j < 16; ++j) { float v = row[bg * 16 + j]; if (v > m) { m = v; mi = bg * 16 + j; } }
; #pragma unroll
;       for (int g = 0; g < 8; ++g) { gm[g] = (g == bg) ? m : gm[g]; gi[g] = (g == bg) ? mi : gi[g]; }
;     }
	v_cmp_gt_f32_e64 s[8:9], v17, v16
	v_cmp_gt_f32_e64 s[10:11], v19, v18
	v_cmp_gt_f32_e64 s[12:13], v21, v20
	v_cmp_gt_f32_e64 s[24:25], v23, v22
	v_cmp_gt_f32_e64 s[26:27], v25, v24
	v_cmp_gt_f32_e64 s[28:29], v27, v26
	v_cmp_gt_f32_e64 s[30:31], v29, v28
	v_cmp_gt_f32_e64 s[34:35], v31, v30
	v_cndmask_b32_e64 v16, v16, v17, s[8:9]
	v_cndmask_b32_e64 v32, 0, 1, s[8:9]
	v_cndmask_b32_e64 v18, v18, v19, s[10:11]
	v_cndmask_b32_e64 v33, 2, 3, s[10:11]
	v_cndmask_b32_e64 v20, v20, v21, s[12:13]
	v_cndmask_b32_e64 v34, 4, 5, s[12:13]
	v_cndmask_b32_e64 v22, v22, v23, s[24:25]
	v_cndmask_b32_e64 v35, 6, 7, s[24:25]
	v_cndmask_b32_e64 v24, v24, v25, s[26:27]
	v_cndmask_b32_e64 v36, 8, 9, s[26:27]
	v_cndmask_b32_e64 v26, v26, v27, s[28:29]
	v_cndmask_b32_e64 v37, 10, 11, s[28:29]
	v_cndmask_b32_e64 v28, v28, v29, s[30:31]
	v_cndmask_b32_e64 v38, 12, 13, s[30:31]
	v_cndmask_b32_e64 v30, v30, v31, s[34:35]
	v_cndmask_b32_e64 v39, 14, 15, s[34:35]
	v_cmp_gt_f32_e64 s[8:9], v18, v16
	v_cmp_gt_f32_e64 s[10:11], v22, v20
	v_cmp_gt_f32_e64 s[12:13], v26, v24
	v_cmp_gt_f32_e64 s[24:25], v30, v28
	v_cndmask_b32_e64 v16, v16, v18, s[8:9]
	v_cndmask_b32_e64 v32, v32, v33, s[8:9]
	v_cndmask_b32_e64 v20, v20, v22, s[10:11]
	v_cndmask_b32_e64 v34, v34, v35, s[10:11]
	v_cndmask_b32_e64 v24, v24, v26, s[12:13]
	v_cndmask_b32_e64 v36, v36, v37, s[12:13]
	v_cndmask_b32_e64 v28, v28, v30, s[24:25]
	v_cndmask_b32_e64 v38, v38, v39, s[24:25]
	v_cmp_gt_f32_e64 s[8:9], v20, v16
	v_cmp_gt_f32_e64 s[10:11], v28, v24
	s_nop 0
	v_cndmask_b32_e64 v16, v16, v20, s[8:9]
	v_cndmask_b32_e64 v32, v32, v34, s[8:9]
	v_cndmask_b32_e64 v24, v24, v28, s[10:11]
	v_cndmask_b32_e64 v36, v36, v38, s[10:11]
	v_cmp_gt_f32_e64 s[8:9], v24, v16
	s_nop 1
	v_cndmask_b32_e64 v16, v16, v24, s[8:9]
	v_cndmask_b32_e64 v32, v32, v36, s[8:9]
	v_lshl_add_u32 v148, v44, 4, v32
	v_cmp_eq_u32_e64 s[8:9], 0, v44
	v_cmp_eq_u32_e64 s[10:11], 1, v44
	v_cmp_eq_u32_e64 s[12:13], 2, v44
	v_cmp_eq_u32_e64 s[24:25], 3, v44
	v_cmp_eq_u32_e64 s[26:27], 4, v44
	v_cmp_eq_u32_e64 s[28:29], 5, v44
	v_cmp_eq_u32_e64 s[30:31], 6, v44
	v_cmp_eq_u32_e64 s[34:35], 7, v44
	v_cndmask_b32_e64 v0, v0, v16, s[8:9]
	v_cndmask_b32_e64 v8, v8, v148, s[8:9]
	v_cndmask_b32_e64 v1, v1, v16, s[10:11]
	v_cndmask_b32_e64 v9, v9, v148, s[10:11]
	v_cndmask_b32_e64 v2, v2, v16, s[12:13]
	v_cndmask_b32_e64 v10, v10, v148, s[12:13]
	v_cndmask_b32_e64 v3, v3, v16, s[24:25]
	v_cndmask_b32_e64 v11, v11, v148, s[24:25]
	v_cndmask_b32_e64 v4, v4, v16, s[26:27]
	v_cndmask_b32_e64 v12, v12, v148, s[26:27]
	v_cndmask_b32_e64 v5, v5, v16, s[28:29]
	v_cndmask_b32_e64 v13, v13, v148, s[28:29]
	v_cndmask_b32_e64 v6, v6, v16, s[30:31]
	v_cndmask_b32_e64 v14, v14, v148, s[30:31]
	v_cndmask_b32_e64 v7, v7, v16, s[34:35]
	v_cndmask_b32_e64 v15, v15, v148, s[34:35]
	v_cmp_gt_f32_e64 s[8:9], v1, v0
	v_cmp_gt_f32_e64 s[10:11], v3, v2
	v_cmp_gt_f32_e64 s[12:13], v5, v4
	v_cmp_gt_f32_e64 s[24:25], v7, v6
	v_cndmask_b32_e64 v40, v0, v1, s[8:9]
	v_cndmask_b32_e64 v44, 0, 1, s[8:9]
	v_cndmask_b32_e64 v141, v8, v9, s[8:9]
	v_cndmask_b32_e64 v41, v2, v3, s[10:11]
	v_cndmask_b32_e64 v45, 2, 3, s[10:11]
	v_cndmask_b32_e64 v142, v10, v11, s[10:11]
	v_cndmask_b32_e64 v42, v4, v5, s[12:13]
	v_cndmask_b32_e64 v46, 4, 5, s[12:13]
	v_cndmask_b32_e64 v143, v12, v13, s[12:13]
	v_cndmask_b32_e64 v43, v6, v7, s[24:25]
	v_cndmask_b32_e64 v47, 6, 7, s[24:25]
	v_cndmask_b32_e64 v144, v14, v15, s[24:25]
	v_cmp_gt_f32_e64 s[8:9], v41, v40
	v_cmp_gt_f32_e64 s[10:11], v43, v42
	s_nop 0
	v_cndmask_b32_e64 v40, v40, v41, s[8:9]
	v_cndmask_b32_e64 v44, v44, v45, s[8:9]
	v_cndmask_b32_e64 v141, v141, v142, s[8:9]
	v_cndmask_b32_e64 v42, v42, v43, s[10:11]
	v_cndmask_b32_e64 v46, v46, v47, s[10:11]
	v_cndmask_b32_e64 v143, v143, v144, s[10:11]
	v_cmp_gt_f32_e64 s[8:9], v42, v40
	s_nop 1
	v_cndmask_b32_e64 v40, v40, v42, s[8:9]
	v_cndmask_b32_e64 v44, v44, v46, s[8:9]
	v_cndmask_b32_e64 v141, v141, v143, s[8:9]
	ds_write_b32 v55, v40 offset:28
	ds_write_b8 v57, v141 offset:7
	v_lshl_add_u32 v146, v141, 2, v54
	ds_write_b32 v146, v60
	v_lshl_add_u32 v147, v44, 6, v54
	ds_read2_b32 v[16:17], v147 offset0:0 offset1:1
	ds_read2_b32 v[18:19], v147 offset0:2 offset1:3
	ds_read2_b32 v[20:21], v147 offset0:4 offset1:5
	ds_read2_b32 v[22:23], v147 offset0:6 offset1:7
	ds_read2_b32 v[24:25], v147 offset0:8 offset1:9
	ds_read2_b32 v[26:27], v147 offset0:10 offset1:11
	ds_read2_b32 v[28:29], v147 offset0:12 offset1:13
	ds_read2_b32 v[30:31], v147 offset0:14 offset1:15
	s_waitcnt lgkmcnt(0)
; DI void peer_topk_item(const Params& p, int tt128, int head, char* smem) {
;     ...
; #pragma unroll 1
;     for (int r = 0; r < 16; ++r) {
;       float best = gm[0]; int bg = 0; int bi = gi[0];
; #pragma unroll
;       for (int g = 1; g < 8; ++g) if (gm[g] > best) { best = gm[g]; bg = g; bi = gi[g]; }
;       topv[tid * 16 + r] = best; topi[tid * 16 + r] = (unsigned char)bi;
;       row[bi] = -INFINITY;
;       float m = -INFINITY; int mi = bg * 16;
; #pragma unroll
;       for (int j = 0; j < 16; ++j) { float v = row[bg * 16 + j]; if (v > m) { m = v; mi = bg * 16 + j; } }
; #pragma unroll
;       for (int g = 0; g < 8; ++g) { gm[g] = (g == bg) ? m : gm[g]; gi[g] = (g == bg) ? mi : gi[g]; }
;     }
	v_cmp_gt_f32_e64 s[8:9], v17, v16
	v_cmp_gt_f32_e64 s[10:11], v19, v18
	v_cmp_gt_f32_e64 s[12:13], v21, v20
	v_cmp_gt_f32_e64 s[24:25], v23, v22
	v_cmp_gt_f32_e64 s[26:27], v25, v24
	v_cmp_gt_f32_e64 s[28:29], v27, v26
	v_cmp_gt_f32_e64 s[30:31], v29, v28
	v_cmp_gt_f32_e64 s[34:35], v31, v30
	v_cndmask_b32_e64 v16, v16, v17, s[8:9]
	v_cndmask_b32_e64 v32, 0, 1, s[8:9]
	v_cndmask_b32_e64 v18, v18, v19, s[10:11]
	v_cndmask_b32_e64 v33, 2, 3, s[10:11]
	v_cndmask_b32_e64 v20, v20, v21, s[12:13]
	v_cndmask_b32_e64 v34, 4, 5, s[12:13]
	v_cndmask_b32_e64 v22, v22, v23, s[24:25]
	v_cndmask_b32_e64 v35, 6, 7, s[24:25]
	v_cndmask_b32_e64 v24, v24, v25, s[26:27]
	v_cndmask_b32_e64 v36, 8, 9, s[26:27]
	v_cndmask_b32_e64 v26, v26, v27, s[28:29]
	v_cndmask_b32_e64 v37, 10, 11, s[28:29]
	v_cndmask_b32_e64 v28, v28, v29, s[30:31]
	v_cndmask_b32_e64 v38, 12, 13, s[30:31]
	v_cndmask_b32_e64 v30, v30, v31, s[34:35]
	v_cndmask_b32_e64 v39, 14, 15, s[34:35]
	v_cmp_gt_f32_e64 s[8:9], v18, v16
	v_cmp_gt_f32_e64 s[10:11], v22, v20
	v_cmp_gt_f32_e64 s[12:13], v26, v24
	v_cmp_gt_f32_e64 s[24:25], v30, v28
	v_cndmask_b32_e64 v16, v16, v18, s[8:9]
	v_cndmask_b32_e64 v32, v32, v33, s[8:9]
	v_cndmask_b32_e64 v20, v20, v22, s[10:11]
	v_cndmask_b32_e64 v34, v34, v35, s[10:11]
	v_cndmask_b32_e64 v24, v24, v26, s[12:13]
	v_cndmask_b32_e64 v36, v36, v37, s[12:13]
	v_cndmask_b32_e64 v28, v28, v30, s[24:25]
	v_cndmask_b32_e64 v38, v38, v39, s[24:25]
	v_cmp_gt_f32_e64 s[8:9], v20, v16
	v_cmp_gt_f32_e64 s[10:11], v28, v24
	s_nop 0
	v_cndmask_b32_e64 v16, v16, v20, s[8:9]
	v_cndmask_b32_e64 v32, v32, v34, s[8:9]
	v_cndmask_b32_e64 v24, v24, v28, s[10:11]
	v_cndmask_b32_e64 v36, v36, v38, s[10:11]
	v_cmp_gt_f32_e64 s[8:9], v24, v16
	s_nop 1
	v_cndmask_b32_e64 v16, v16, v24, s[8:9]
	v_cndmask_b32_e64 v32, v32, v36, s[8:9]
	v_lshl_add_u32 v148, v44, 4, v32
	v_cmp_eq_u32_e64 s[8:9], 0, v44
	v_cmp_eq_u32_e64 s[10:11], 1, v44
	v_cmp_eq_u32_e64 s[12:13], 2, v44
	v_cmp_eq_u32_e64 s[24:25], 3, v44
	v_cmp_eq_u32_e64 s[26:27], 4, v44
	v_cmp_eq_u32_e64 s[28:29], 5, v44
	v_cmp_eq_u32_e64 s[30:31], 6, v44
	v_cmp_eq_u32_e64 s[34:35], 7, v44
	v_cndmask_b32_e64 v0, v0, v16, s[8:9]
	v_cndmask_b32_e64 v8, v8, v148, s[8:9]
	v_cndmask_b32_e64 v1, v1, v16, s[10:11]
	v_cndmask_b32_e64 v9, v9, v148, s[10:11]
	v_cndmask_b32_e64 v2, v2, v16, s[12:13]
	v_cndmask_b32_e64 v10, v10, v148, s[12:13]
	v_cndmask_b32_e64 v3, v3, v16, s[24:25]
	v_cndmask_b32_e64 v11, v11, v148, s[24:25]
	v_cndmask_b32_e64 v4, v4, v16, s[26:27]
	v_cndmask_b32_e64 v12, v12, v148, s[26:27]
	v_cndmask_b32_e64 v5, v5, v16, s[28:29]
	v_cndmask_b32_e64 v13, v13, v148, s[28:29]
	v_cndmask_b32_e64 v6, v6, v16, s[30:31]
	v_cndmask_b32_e64 v14, v14, v148, s[30:31]
	v_cndmask_b32_e64 v7, v7, v16, s[34:35]
	v_cndmask_b32_e64 v15, v15, v148, s[34:35]
	v_cmp_gt_f32_e64 s[8:9], v1, v0
	v_cmp_gt_f32_e64 s[10:11], v3, v2
	v_cmp_gt_f32_e64 s[12:13], v5, v4
	v_cmp_gt_f32_e64 s[24:25], v7, v6
	v_cndmask_b32_e64 v40, v0, v1, s[8:9]
	v_cndmask_b32_e64 v44, 0, 1, s[8:9]
	v_cndmask_b32_e64 v141, v8, v9, s[8:9]
	v_cndmask_b32_e64 v41, v2, v3, s[10:11]
	v_cndmask_b32_e64 v45, 2, 3, s[10:11]
	v_cndmask_b32_e64 v142, v10, v11, s[10:11]
	v_cndmask_b32_e64 v42, v4, v5, s[12:13]
	v_cndmask_b32_e64 v46, 4, 5, s[12:13]
	v_cndmask_b32_e64 v143, v12, v13, s[12:13]
	v_cndmask_b32_e64 v43, v6, v7, s[24:25]
	v_cndmask_b32_e64 v47, 6, 7, s[24:25]
	v_cndmask_b32_e64 v144, v14, v15, s[24:25]
	v_cmp_gt_f32_e64 s[8:9], v41, v40
	v_cmp_gt_f32_e64 s[10:11], v43, v42
	s_nop 0
	v_cndmask_b32_e64 v40, v40, v41, s[8:9]
	v_cndmask_b32_e64 v44, v44, v45, s[8:9]
	v_cndmask_b32_e64 v141, v141, v142, s[8:9]
	v_cndmask_b32_e64 v42, v42, v43, s[10:11]
	v_cndmask_b32_e64 v46, v46, v47, s[10:11]
	v_cndmask_b32_e64 v143, v143, v144, s[10:11]
	v_cmp_gt_f32_e64 s[8:9], v42, v40
	s_nop 1
	v_cndmask_b32_e64 v40, v40, v42, s[8:9]
	v_cndmask_b32_e64 v44, v44, v46, s[8:9]
	v_cndmask_b32_e64 v141, v141, v143, s[8:9]
	ds_write_b32 v55, v40 offset:32
	ds_write_b8 v57, v141 offset:8
	v_lshl_add_u32 v146, v141, 2, v54
	ds_write_b32 v146, v60
	v_lshl_add_u32 v147, v44, 6, v54
	ds_read2_b32 v[16:17], v147 offset0:0 offset1:1
	ds_read2_b32 v[18:19], v147 offset0:2 offset1:3
	ds_read2_b32 v[20:21], v147 offset0:4 offset1:5
	ds_read2_b32 v[22:23], v147 offset0:6 offset1:7
	ds_read2_b32 v[24:25], v147 offset0:8 offset1:9
	ds_read2_b32 v[26:27], v147 offset0:10 offset1:11
	ds_read2_b32 v[28:29], v147 offset0:12 offset1:13
	ds_read2_b32 v[30:31], v147 offset0:14 offset1:15
	s_waitcnt lgkmcnt(0)
; DI void peer_topk_item(const Params& p, int tt128, int head, char* smem) {
;     ...
; #pragma unroll 1
;     for (int r = 0; r < 16; ++r) {
;       float best = gm[0]; int bg = 0; int bi = gi[0];
; #pragma unroll
;       for (int g = 1; g < 8; ++g) if (gm[g] > best) { best = gm[g]; bg = g; bi = gi[g]; }
;       topv[tid * 16 + r] = best; topi[tid * 16 + r] = (unsigned char)bi;
;       row[bi] = -INFINITY;
;       float m = -INFINITY; int mi = bg * 16;
; #pragma unroll
;       for (int j = 0; j < 16; ++j) { float v = row[bg * 16 + j]; if (v > m) { m = v; mi = bg * 16 + j; } }
; #pragma unroll
;       for (int g = 0; g < 8; ++g) { gm[g] = (g == bg) ? m : gm[g]; gi[g] = (g == bg) ? mi : gi[g]; }
;     }
	v_cmp_gt_f32_e64 s[8:9], v17, v16
	v_cmp_gt_f32_e64 s[10:11], v19, v18
	v_cmp_gt_f32_e64 s[12:13], v21, v20
	v_cmp_gt_f32_e64 s[24:25], v23, v22
	v_cmp_gt_f32_e64 s[26:27], v25, v24
	v_cmp_gt_f32_e64 s[28:29], v27, v26
	v_cmp_gt_f32_e64 s[30:31], v29, v28
	v_cmp_gt_f32_e64 s[34:35], v31, v30
	v_cndmask_b32_e64 v16, v16, v17, s[8:9]
	v_cndmask_b32_e64 v32, 0, 1, s[8:9]
	v_cndmask_b32_e64 v18, v18, v19, s[10:11]
	v_cndmask_b32_e64 v33, 2, 3, s[10:11]
	v_cndmask_b32_e64 v20, v20, v21, s[12:13]
	v_cndmask_b32_e64 v34, 4, 5, s[12:13]
	v_cndmask_b32_e64 v22, v22, v23, s[24:25]
	v_cndmask_b32_e64 v35, 6, 7, s[24:25]
	v_cndmask_b32_e64 v24, v24, v25, s[26:27]
	v_cndmask_b32_e64 v36, 8, 9, s[26:27]
	v_cndmask_b32_e64 v26, v26, v27, s[28:29]
	v_cndmask_b32_e64 v37, 10, 11, s[28:29]
	v_cndmask_b32_e64 v28, v28, v29, s[30:31]
	v_cndmask_b32_e64 v38, 12, 13, s[30:31]
	v_cndmask_b32_e64 v30, v30, v31, s[34:35]
	v_cndmask_b32_e64 v39, 14, 15, s[34:35]
	v_cmp_gt_f32_e64 s[8:9], v18, v16
	v_cmp_gt_f32_e64 s[10:11], v22, v20
	v_cmp_gt_f32_e64 s[12:13], v26, v24
	v_cmp_gt_f32_e64 s[24:25], v30, v28
	v_cndmask_b32_e64 v16, v16, v18, s[8:9]
	v_cndmask_b32_e64 v32, v32, v33, s[8:9]
	v_cndmask_b32_e64 v20, v20, v22, s[10:11]
	v_cndmask_b32_e64 v34, v34, v35, s[10:11]
	v_cndmask_b32_e64 v24, v24, v26, s[12:13]
	v_cndmask_b32_e64 v36, v36, v37, s[12:13]
	v_cndmask_b32_e64 v28, v28, v30, s[24:25]
	v_cndmask_b32_e64 v38, v38, v39, s[24:25]
	v_cmp_gt_f32_e64 s[8:9], v20, v16
	v_cmp_gt_f32_e64 s[10:11], v28, v24
	s_nop 0
	v_cndmask_b32_e64 v16, v16, v20, s[8:9]
	v_cndmask_b32_e64 v32, v32, v34, s[8:9]
	v_cndmask_b32_e64 v24, v24, v28, s[10:11]
	v_cndmask_b32_e64 v36, v36, v38, s[10:11]
	v_cmp_gt_f32_e64 s[8:9], v24, v16
	s_nop 1
	v_cndmask_b32_e64 v16, v16, v24, s[8:9]
	v_cndmask_b32_e64 v32, v32, v36, s[8:9]
	v_lshl_add_u32 v148, v44, 4, v32
	v_cmp_eq_u32_e64 s[8:9], 0, v44
	v_cmp_eq_u32_e64 s[10:11], 1, v44
	v_cmp_eq_u32_e64 s[12:13], 2, v44
	v_cmp_eq_u32_e64 s[24:25], 3, v44
	v_cmp_eq_u32_e64 s[26:27], 4, v44
	v_cmp_eq_u32_e64 s[28:29], 5, v44
	v_cmp_eq_u32_e64 s[30:31], 6, v44
	v_cmp_eq_u32_e64 s[34:35], 7, v44
	v_cndmask_b32_e64 v0, v0, v16, s[8:9]
	v_cndmask_b32_e64 v8, v8, v148, s[8:9]
	v_cndmask_b32_e64 v1, v1, v16, s[10:11]
	v_cndmask_b32_e64 v9, v9, v148, s[10:11]
	v_cndmask_b32_e64 v2, v2, v16, s[12:13]
	v_cndmask_b32_e64 v10, v10, v148, s[12:13]
	v_cndmask_b32_e64 v3, v3, v16, s[24:25]
	v_cndmask_b32_e64 v11, v11, v148, s[24:25]
	v_cndmask_b32_e64 v4, v4, v16, s[26:27]
	v_cndmask_b32_e64 v12, v12, v148, s[26:27]
	v_cndmask_b32_e64 v5, v5, v16, s[28:29]
	v_cndmask_b32_e64 v13, v13, v148, s[28:29]
	v_cndmask_b32_e64 v6, v6, v16, s[30:31]
	v_cndmask_b32_e64 v14, v14, v148, s[30:31]
	v_cndmask_b32_e64 v7, v7, v16, s[34:35]
	v_cndmask_b32_e64 v15, v15, v148, s[34:35]
	v_cmp_gt_f32_e64 s[8:9], v1, v0
	v_cmp_gt_f32_e64 s[10:11], v3, v2
	v_cmp_gt_f32_e64 s[12:13], v5, v4
	v_cmp_gt_f32_e64 s[24:25], v7, v6
	v_cndmask_b32_e64 v40, v0, v1, s[8:9]
	v_cndmask_b32_e64 v44, 0, 1, s[8:9]
	v_cndmask_b32_e64 v141, v8, v9, s[8:9]
	v_cndmask_b32_e64 v41, v2, v3, s[10:11]
	v_cndmask_b32_e64 v45, 2, 3, s[10:11]
	v_cndmask_b32_e64 v142, v10, v11, s[10:11]
	v_cndmask_b32_e64 v42, v4, v5, s[12:13]
	v_cndmask_b32_e64 v46, 4, 5, s[12:13]
	v_cndmask_b32_e64 v143, v12, v13, s[12:13]
	v_cndmask_b32_e64 v43, v6, v7, s[24:25]
	v_cndmask_b32_e64 v47, 6, 7, s[24:25]
	v_cndmask_b32_e64 v144, v14, v15, s[24:25]
	v_cmp_gt_f32_e64 s[8:9], v41, v40
	v_cmp_gt_f32_e64 s[10:11], v43, v42
	s_nop 0
	v_cndmask_b32_e64 v40, v40, v41, s[8:9]
	v_cndmask_b32_e64 v44, v44, v45, s[8:9]
	v_cndmask_b32_e64 v141, v141, v142, s[8:9]
	v_cndmask_b32_e64 v42, v42, v43, s[10:11]
	v_cndmask_b32_e64 v46, v46, v47, s[10:11]
	v_cndmask_b32_e64 v143, v143, v144, s[10:11]
	v_cmp_gt_f32_e64 s[8:9], v42, v40
	s_nop 1
	v_cndmask_b32_e64 v40, v40, v42, s[8:9]
	v_cndmask_b32_e64 v44, v44, v46, s[8:9]
	v_cndmask_b32_e64 v141, v141, v143, s[8:9]
	ds_write_b32 v55, v40 offset:36
	ds_write_b8 v57, v141 offset:9
	v_lshl_add_u32 v146, v141, 2, v54
	ds_write_b32 v146, v60
	v_lshl_add_u32 v147, v44, 6, v54
	ds_read2_b32 v[16:17], v147 offset0:0 offset1:1
	ds_read2_b32 v[18:19], v147 offset0:2 offset1:3
	ds_read2_b32 v[20:21], v147 offset0:4 offset1:5
	ds_read2_b32 v[22:23], v147 offset0:6 offset1:7
	ds_read2_b32 v[24:25], v147 offset0:8 offset1:9
	ds_read2_b32 v[26:27], v147 offset0:10 offset1:11
	ds_read2_b32 v[28:29], v147 offset0:12 offset1:13
	ds_read2_b32 v[30:31], v147 offset0:14 offset1:15
	s_waitcnt lgkmcnt(0)
; DI void peer_topk_item(const Params& p, int tt128, int head, char* smem) {
;     ...
; #pragma unroll 1
;     for (int r = 0; r < 16; ++r) {
;       float best = gm[0]; int bg = 0; int bi = gi[0];
; #pragma unroll
;       for (int g = 1; g < 8; ++g) if (gm[g] > best) { best = gm[g]; bg = g; bi = gi[g]; }
;       topv[tid * 16 + r] = best; topi[tid * 16 + r] = (unsigned char)bi;
;       row[bi] = -INFINITY;
;       float m = -INFINITY; int mi = bg * 16;
; #pragma unroll
;       for (int j = 0; j < 16; ++j) { float v = row[bg * 16 + j]; if (v > m) { m = v; mi = bg * 16 + j; } }
; #pragma unroll
;       for (int g = 0; g < 8; ++g) { gm[g] = (g == bg) ? m : gm[g]; gi[g] = (g == bg) ? mi : gi[g]; }
;     }
	v_cmp_gt_f32_e64 s[8:9], v17, v16
	v_cmp_gt_f32_e64 s[10:11], v19, v18
	v_cmp_gt_f32_e64 s[12:13], v21, v20
	v_cmp_gt_f32_e64 s[24:25], v23, v22
	v_cmp_gt_f32_e64 s[26:27], v25, v24
	v_cmp_gt_f32_e64 s[28:29], v27, v26
	v_cmp_gt_f32_e64 s[30:31], v29, v28
	v_cmp_gt_f32_e64 s[34:35], v31, v30
	v_cndmask_b32_e64 v16, v16, v17, s[8:9]
	v_cndmask_b32_e64 v32, 0, 1, s[8:9]
	v_cndmask_b32_e64 v18, v18, v19, s[10:11]
	v_cndmask_b32_e64 v33, 2, 3, s[10:11]
	v_cndmask_b32_e64 v20, v20, v21, s[12:13]
	v_cndmask_b32_e64 v34, 4, 5, s[12:13]
	v_cndmask_b32_e64 v22, v22, v23, s[24:25]
	v_cndmask_b32_e64 v35, 6, 7, s[24:25]
	v_cndmask_b32_e64 v24, v24, v25, s[26:27]
	v_cndmask_b32_e64 v36, 8, 9, s[26:27]
	v_cndmask_b32_e64 v26, v26, v27, s[28:29]
	v_cndmask_b32_e64 v37, 10, 11, s[28:29]
	v_cndmask_b32_e64 v28, v28, v29, s[30:31]
	v_cndmask_b32_e64 v38, 12, 13, s[30:31]
	v_cndmask_b32_e64 v30, v30, v31, s[34:35]
	v_cndmask_b32_e64 v39, 14, 15, s[34:35]
	v_cmp_gt_f32_e64 s[8:9], v18, v16
	v_cmp_gt_f32_e64 s[10:11], v22, v20
	v_cmp_gt_f32_e64 s[12:13], v26, v24
	v_cmp_gt_f32_e64 s[24:25], v30, v28
	v_cndmask_b32_e64 v16, v16, v18, s[8:9]
	v_cndmask_b32_e64 v32, v32, v33, s[8:9]
	v_cndmask_b32_e64 v20, v20, v22, s[10:11]
	v_cndmask_b32_e64 v34, v34, v35, s[10:11]
	v_cndmask_b32_e64 v24, v24, v26, s[12:13]
	v_cndmask_b32_e64 v36, v36, v37, s[12:13]
	v_cndmask_b32_e64 v28, v28, v30, s[24:25]
	v_cndmask_b32_e64 v38, v38, v39, s[24:25]
	v_cmp_gt_f32_e64 s[8:9], v20, v16
	v_cmp_gt_f32_e64 s[10:11], v28, v24
	s_nop 0
	v_cndmask_b32_e64 v16, v16, v20, s[8:9]
	v_cndmask_b32_e64 v32, v32, v34, s[8:9]
	v_cndmask_b32_e64 v24, v24, v28, s[10:11]
	v_cndmask_b32_e64 v36, v36, v38, s[10:11]
	v_cmp_gt_f32_e64 s[8:9], v24, v16
	s_nop 1
	v_cndmask_b32_e64 v16, v16, v24, s[8:9]
	v_cndmask_b32_e64 v32, v32, v36, s[8:9]
	v_lshl_add_u32 v148, v44, 4, v32
	v_cmp_eq_u32_e64 s[8:9], 0, v44
	v_cmp_eq_u32_e64 s[10:11], 1, v44
	v_cmp_eq_u32_e64 s[12:13], 2, v44
	v_cmp_eq_u32_e64 s[24:25], 3, v44
	v_cmp_eq_u32_e64 s[26:27], 4, v44
	v_cmp_eq_u32_e64 s[28:29], 5, v44
	v_cmp_eq_u32_e64 s[30:31], 6, v44
	v_cmp_eq_u32_e64 s[34:35], 7, v44
	v_cndmask_b32_e64 v0, v0, v16, s[8:9]
	v_cndmask_b32_e64 v8, v8, v148, s[8:9]
	v_cndmask_b32_e64 v1, v1, v16, s[10:11]
	v_cndmask_b32_e64 v9, v9, v148, s[10:11]
	v_cndmask_b32_e64 v2, v2, v16, s[12:13]
	v_cndmask_b32_e64 v10, v10, v148, s[12:13]
	v_cndmask_b32_e64 v3, v3, v16, s[24:25]
	v_cndmask_b32_e64 v11, v11, v148, s[24:25]
	v_cndmask_b32_e64 v4, v4, v16, s[26:27]
	v_cndmask_b32_e64 v12, v12, v148, s[26:27]
	v_cndmask_b32_e64 v5, v5, v16, s[28:29]
	v_cndmask_b32_e64 v13, v13, v148, s[28:29]
	v_cndmask_b32_e64 v6, v6, v16, s[30:31]
	v_cndmask_b32_e64 v14, v14, v148, s[30:31]
	v_cndmask_b32_e64 v7, v7, v16, s[34:35]
	v_cndmask_b32_e64 v15, v15, v148, s[34:35]
	v_cmp_gt_f32_e64 s[8:9], v1, v0
	v_cmp_gt_f32_e64 s[10:11], v3, v2
	v_cmp_gt_f32_e64 s[12:13], v5, v4
	v_cmp_gt_f32_e64 s[24:25], v7, v6
	v_cndmask_b32_e64 v40, v0, v1, s[8:9]
	v_cndmask_b32_e64 v44, 0, 1, s[8:9]
	v_cndmask_b32_e64 v141, v8, v9, s[8:9]
	v_cndmask_b32_e64 v41, v2, v3, s[10:11]
	v_cndmask_b32_e64 v45, 2, 3, s[10:11]
	v_cndmask_b32_e64 v142, v10, v11, s[10:11]
	v_cndmask_b32_e64 v42, v4, v5, s[12:13]
	v_cndmask_b32_e64 v46, 4, 5, s[12:13]
	v_cndmask_b32_e64 v143, v12, v13, s[12:13]
	v_cndmask_b32_e64 v43, v6, v7, s[24:25]
	v_cndmask_b32_e64 v47, 6, 7, s[24:25]
	v_cndmask_b32_e64 v144, v14, v15, s[24:25]
	v_cmp_gt_f32_e64 s[8:9], v41, v40
	v_cmp_gt_f32_e64 s[10:11], v43, v42
	s_nop 0
	v_cndmask_b32_e64 v40, v40, v41, s[8:9]
	v_cndmask_b32_e64 v44, v44, v45, s[8:9]
	v_cndmask_b32_e64 v141, v141, v142, s[8:9]
	v_cndmask_b32_e64 v42, v42, v43, s[10:11]
	v_cndmask_b32_e64 v46, v46, v47, s[10:11]
	v_cndmask_b32_e64 v143, v143, v144, s[10:11]
	v_cmp_gt_f32_e64 s[8:9], v42, v40
	s_nop 1
	v_cndmask_b32_e64 v40, v40, v42, s[8:9]
	v_cndmask_b32_e64 v44, v44, v46, s[8:9]
	v_cndmask_b32_e64 v141, v141, v143, s[8:9]
	ds_write_b32 v55, v40 offset:40
	ds_write_b8 v57, v141 offset:10
	v_lshl_add_u32 v146, v141, 2, v54
	ds_write_b32 v146, v60
	v_lshl_add_u32 v147, v44, 6, v54
	ds_read2_b32 v[16:17], v147 offset0:0 offset1:1
	ds_read2_b32 v[18:19], v147 offset0:2 offset1:3
	ds_read2_b32 v[20:21], v147 offset0:4 offset1:5
	ds_read2_b32 v[22:23], v147 offset0:6 offset1:7
	ds_read2_b32 v[24:25], v147 offset0:8 offset1:9
	ds_read2_b32 v[26:27], v147 offset0:10 offset1:11
	ds_read2_b32 v[28:29], v147 offset0:12 offset1:13
	ds_read2_b32 v[30:31], v147 offset0:14 offset1:15
	s_waitcnt lgkmcnt(0)
; DI void peer_topk_item(const Params& p, int tt128, int head, char* smem) {
;     ...
; #pragma unroll 1
;     for (int r = 0; r < 16; ++r) {
;       float best = gm[0]; int bg = 0; int bi = gi[0];
; #pragma unroll
;       for (int g = 1; g < 8; ++g) if (gm[g] > best) { best = gm[g]; bg = g; bi = gi[g]; }
;       topv[tid * 16 + r] = best; topi[tid * 16 + r] = (unsigned char)bi;
;       row[bi] = -INFINITY;
;       float m = -INFINITY; int mi = bg * 16;
; #pragma unroll
;       for (int j = 0; j < 16; ++j) { float v = row[bg * 16 + j]; if (v > m) { m = v; mi = bg * 16 + j; } }
; #pragma unroll
;       for (int g = 0; g < 8; ++g) { gm[g] = (g == bg) ? m : gm[g]; gi[g] = (g == bg) ? mi : gi[g]; }
;     }
	v_cmp_gt_f32_e64 s[8:9], v17, v16
	v_cmp_gt_f32_e64 s[10:11], v19, v18
	v_cmp_gt_f32_e64 s[12:13], v21, v20
	v_cmp_gt_f32_e64 s[24:25], v23, v22
	v_cmp_gt_f32_e64 s[26:27], v25, v24
	v_cmp_gt_f32_e64 s[28:29], v27, v26
	v_cmp_gt_f32_e64 s[30:31], v29, v28
	v_cmp_gt_f32_e64 s[34:35], v31, v30
	v_cndmask_b32_e64 v16, v16, v17, s[8:9]
	v_cndmask_b32_e64 v32, 0, 1, s[8:9]
	v_cndmask_b32_e64 v18, v18, v19, s[10:11]
	v_cndmask_b32_e64 v33, 2, 3, s[10:11]
	v_cndmask_b32_e64 v20, v20, v21, s[12:13]
	v_cndmask_b32_e64 v34, 4, 5, s[12:13]
	v_cndmask_b32_e64 v22, v22, v23, s[24:25]
	v_cndmask_b32_e64 v35, 6, 7, s[24:25]
	v_cndmask_b32_e64 v24, v24, v25, s[26:27]
	v_cndmask_b32_e64 v36, 8, 9, s[26:27]
	v_cndmask_b32_e64 v26, v26, v27, s[28:29]
	v_cndmask_b32_e64 v37, 10, 11, s[28:29]
	v_cndmask_b32_e64 v28, v28, v29, s[30:31]
	v_cndmask_b32_e64 v38, 12, 13, s[30:31]
	v_cndmask_b32_e64 v30, v30, v31, s[34:35]
	v_cndmask_b32_e64 v39, 14, 15, s[34:35]
	v_cmp_gt_f32_e64 s[8:9], v18, v16
	v_cmp_gt_f32_e64 s[10:11], v22, v20
	v_cmp_gt_f32_e64 s[12:13], v26, v24
	v_cmp_gt_f32_e64 s[24:25], v30, v28
	v_cndmask_b32_e64 v16, v16, v18, s[8:9]
	v_cndmask_b32_e64 v32, v32, v33, s[8:9]
	v_cndmask_b32_e64 v20, v20, v22, s[10:11]
	v_cndmask_b32_e64 v34, v34, v35, s[10:11]
	v_cndmask_b32_e64 v24, v24, v26, s[12:13]
	v_cndmask_b32_e64 v36, v36, v37, s[12:13]
	v_cndmask_b32_e64 v28, v28, v30, s[24:25]
	v_cndmask_b32_e64 v38, v38, v39, s[24:25]
	v_cmp_gt_f32_e64 s[8:9], v20, v16
	v_cmp_gt_f32_e64 s[10:11], v28, v24
	s_nop 0
	v_cndmask_b32_e64 v16, v16, v20, s[8:9]
	v_cndmask_b32_e64 v32, v32, v34, s[8:9]
	v_cndmask_b32_e64 v24, v24, v28, s[10:11]
	v_cndmask_b32_e64 v36, v36, v38, s[10:11]
	v_cmp_gt_f32_e64 s[8:9], v24, v16
	s_nop 1
	v_cndmask_b32_e64 v16, v16, v24, s[8:9]
	v_cndmask_b32_e64 v32, v32, v36, s[8:9]
	v_lshl_add_u32 v148, v44, 4, v32
	v_cmp_eq_u32_e64 s[8:9], 0, v44
	v_cmp_eq_u32_e64 s[10:11], 1, v44
	v_cmp_eq_u32_e64 s[12:13], 2, v44
	v_cmp_eq_u32_e64 s[24:25], 3, v44
	v_cmp_eq_u32_e64 s[26:27], 4, v44
	v_cmp_eq_u32_e64 s[28:29], 5, v44
	v_cmp_eq_u32_e64 s[30:31], 6, v44
	v_cmp_eq_u32_e64 s[34:35], 7, v44
	v_cndmask_b32_e64 v0, v0, v16, s[8:9]
	v_cndmask_b32_e64 v8, v8, v148, s[8:9]
	v_cndmask_b32_e64 v1, v1, v16, s[10:11]
	v_cndmask_b32_e64 v9, v9, v148, s[10:11]
	v_cndmask_b32_e64 v2, v2, v16, s[12:13]
	v_cndmask_b32_e64 v10, v10, v148, s[12:13]
	v_cndmask_b32_e64 v3, v3, v16, s[24:25]
	v_cndmask_b32_e64 v11, v11, v148, s[24:25]
	v_cndmask_b32_e64 v4, v4, v16, s[26:27]
	v_cndmask_b32_e64 v12, v12, v148, s[26:27]
	v_cndmask_b32_e64 v5, v5, v16, s[28:29]
	v_cndmask_b32_e64 v13, v13, v148, s[28:29]
	v_cndmask_b32_e64 v6, v6, v16, s[30:31]
	v_cndmask_b32_e64 v14, v14, v148, s[30:31]
	v_cndmask_b32_e64 v7, v7, v16, s[34:35]
	v_cndmask_b32_e64 v15, v15, v148, s[34:35]
	v_cmp_gt_f32_e64 s[8:9], v1, v0
	v_cmp_gt_f32_e64 s[10:11], v3, v2
	v_cmp_gt_f32_e64 s[12:13], v5, v4
	v_cmp_gt_f32_e64 s[24:25], v7, v6
	v_cndmask_b32_e64 v40, v0, v1, s[8:9]
	v_cndmask_b32_e64 v44, 0, 1, s[8:9]
	v_cndmask_b32_e64 v141, v8, v9, s[8:9]
	v_cndmask_b32_e64 v41, v2, v3, s[10:11]
	v_cndmask_b32_e64 v45, 2, 3, s[10:11]
	v_cndmask_b32_e64 v142, v10, v11, s[10:11]
	v_cndmask_b32_e64 v42, v4, v5, s[12:13]
	v_cndmask_b32_e64 v46, 4, 5, s[12:13]
	v_cndmask_b32_e64 v143, v12, v13, s[12:13]
	v_cndmask_b32_e64 v43, v6, v7, s[24:25]
	v_cndmask_b32_e64 v47, 6, 7, s[24:25]
	v_cndmask_b32_e64 v144, v14, v15, s[24:25]
	v_cmp_gt_f32_e64 s[8:9], v41, v40
	v_cmp_gt_f32_e64 s[10:11], v43, v42
	s_nop 0
	v_cndmask_b32_e64 v40, v40, v41, s[8:9]
	v_cndmask_b32_e64 v44, v44, v45, s[8:9]
	v_cndmask_b32_e64 v141, v141, v142, s[8:9]
	v_cndmask_b32_e64 v42, v42, v43, s[10:11]
	v_cndmask_b32_e64 v46, v46, v47, s[10:11]
	v_cndmask_b32_e64 v143, v143, v144, s[10:11]
	v_cmp_gt_f32_e64 s[8:9], v42, v40
	s_nop 1
	v_cndmask_b32_e64 v40, v40, v42, s[8:9]
	v_cndmask_b32_e64 v44, v44, v46, s[8:9]
	v_cndmask_b32_e64 v141, v141, v143, s[8:9]
	ds_write_b32 v55, v40 offset:44
	ds_write_b8 v57, v141 offset:11
	v_lshl_add_u32 v146, v141, 2, v54
	ds_write_b32 v146, v60
	v_lshl_add_u32 v147, v44, 6, v54
	ds_read2_b32 v[16:17], v147 offset0:0 offset1:1
	ds_read2_b32 v[18:19], v147 offset0:2 offset1:3
	ds_read2_b32 v[20:21], v147 offset0:4 offset1:5
	ds_read2_b32 v[22:23], v147 offset0:6 offset1:7
	ds_read2_b32 v[24:25], v147 offset0:8 offset1:9
	ds_read2_b32 v[26:27], v147 offset0:10 offset1:11
	ds_read2_b32 v[28:29], v147 offset0:12 offset1:13
	ds_read2_b32 v[30:31], v147 offset0:14 offset1:15
	s_waitcnt lgkmcnt(0)
; DI void peer_topk_item(const Params& p, int tt128, int head, char* smem) {
;     ...
; #pragma unroll 1
;     for (int r = 0; r < 16; ++r) {
;       float best = gm[0]; int bg = 0; int bi = gi[0];
; #pragma unroll
;       for (int g = 1; g < 8; ++g) if (gm[g] > best) { best = gm[g]; bg = g; bi = gi[g]; }
;       topv[tid * 16 + r] = best; topi[tid * 16 + r] = (unsigned char)bi;
;       row[bi] = -INFINITY;
;       float m = -INFINITY; int mi = bg * 16;
; #pragma unroll
;       for (int j = 0; j < 16; ++j) { float v = row[bg * 16 + j]; if (v > m) { m = v; mi = bg * 16 + j; } }
; #pragma unroll
;       for (int g = 0; g < 8; ++g) { gm[g] = (g == bg) ? m : gm[g]; gi[g] = (g == bg) ? mi : gi[g]; }
;     }
	v_cmp_gt_f32_e64 s[8:9], v17, v16
	v_cmp_gt_f32_e64 s[10:11], v19, v18
	v_cmp_gt_f32_e64 s[12:13], v21, v20
	v_cmp_gt_f32_e64 s[24:25], v23, v22
	v_cmp_gt_f32_e64 s[26:27], v25, v24
	v_cmp_gt_f32_e64 s[28:29], v27, v26
	v_cmp_gt_f32_e64 s[30:31], v29, v28
	v_cmp_gt_f32_e64 s[34:35], v31, v30
	v_cndmask_b32_e64 v16, v16, v17, s[8:9]
	v_cndmask_b32_e64 v32, 0, 1, s[8:9]
	v_cndmask_b32_e64 v18, v18, v19, s[10:11]
	v_cndmask_b32_e64 v33, 2, 3, s[10:11]
	v_cndmask_b32_e64 v20, v20, v21, s[12:13]
	v_cndmask_b32_e64 v34, 4, 5, s[12:13]
	v_cndmask_b32_e64 v22, v22, v23, s[24:25]
	v_cndmask_b32_e64 v35, 6, 7, s[24:25]
	v_cndmask_b32_e64 v24, v24, v25, s[26:27]
	v_cndmask_b32_e64 v36, 8, 9, s[26:27]
	v_cndmask_b32_e64 v26, v26, v27, s[28:29]
	v_cndmask_b32_e64 v37, 10, 11, s[28:29]
	v_cndmask_b32_e64 v28, v28, v29, s[30:31]
	v_cndmask_b32_e64 v38, 12, 13, s[30:31]
	v_cndmask_b32_e64 v30, v30, v31, s[34:35]
	v_cndmask_b32_e64 v39, 14, 15, s[34:35]
	v_cmp_gt_f32_e64 s[8:9], v18, v16
	v_cmp_gt_f32_e64 s[10:11], v22, v20
	v_cmp_gt_f32_e64 s[12:13], v26, v24
	v_cmp_gt_f32_e64 s[24:25], v30, v28
	v_cndmask_b32_e64 v16, v16, v18, s[8:9]
	v_cndmask_b32_e64 v32, v32, v33, s[8:9]
	v_cndmask_b32_e64 v20, v20, v22, s[10:11]
	v_cndmask_b32_e64 v34, v34, v35, s[10:11]
	v_cndmask_b32_e64 v24, v24, v26, s[12:13]
	v_cndmask_b32_e64 v36, v36, v37, s[12:13]
	v_cndmask_b32_e64 v28, v28, v30, s[24:25]
	v_cndmask_b32_e64 v38, v38, v39, s[24:25]
	v_cmp_gt_f32_e64 s[8:9], v20, v16
	v_cmp_gt_f32_e64 s[10:11], v28, v24
	s_nop 0
	v_cndmask_b32_e64 v16, v16, v20, s[8:9]
	v_cndmask_b32_e64 v32, v32, v34, s[8:9]
	v_cndmask_b32_e64 v24, v24, v28, s[10:11]
	v_cndmask_b32_e64 v36, v36, v38, s[10:11]
	v_cmp_gt_f32_e64 s[8:9], v24, v16
	s_nop 1
	v_cndmask_b32_e64 v16, v16, v24, s[8:9]
	v_cndmask_b32_e64 v32, v32, v36, s[8:9]
	v_lshl_add_u32 v148, v44, 4, v32
	v_cmp_eq_u32_e64 s[8:9], 0, v44
	v_cmp_eq_u32_e64 s[10:11], 1, v44
	v_cmp_eq_u32_e64 s[12:13], 2, v44
	v_cmp_eq_u32_e64 s[24:25], 3, v44
	v_cmp_eq_u32_e64 s[26:27], 4, v44
	v_cmp_eq_u32_e64 s[28:29], 5, v44
	v_cmp_eq_u32_e64 s[30:31], 6, v44
	v_cmp_eq_u32_e64 s[34:35], 7, v44
	v_cndmask_b32_e64 v0, v0, v16, s[8:9]
	v_cndmask_b32_e64 v8, v8, v148, s[8:9]
	v_cndmask_b32_e64 v1, v1, v16, s[10:11]
	v_cndmask_b32_e64 v9, v9, v148, s[10:11]
	v_cndmask_b32_e64 v2, v2, v16, s[12:13]
	v_cndmask_b32_e64 v10, v10, v148, s[12:13]
	v_cndmask_b32_e64 v3, v3, v16, s[24:25]
	v_cndmask_b32_e64 v11, v11, v148, s[24:25]
	v_cndmask_b32_e64 v4, v4, v16, s[26:27]
	v_cndmask_b32_e64 v12, v12, v148, s[26:27]
	v_cndmask_b32_e64 v5, v5, v16, s[28:29]
	v_cndmask_b32_e64 v13, v13, v148, s[28:29]
	v_cndmask_b32_e64 v6, v6, v16, s[30:31]
	v_cndmask_b32_e64 v14, v14, v148, s[30:31]
	v_cndmask_b32_e64 v7, v7, v16, s[34:35]
	v_cndmask_b32_e64 v15, v15, v148, s[34:35]
	v_cmp_gt_f32_e64 s[8:9], v1, v0
	v_cmp_gt_f32_e64 s[10:11], v3, v2
	v_cmp_gt_f32_e64 s[12:13], v5, v4
	v_cmp_gt_f32_e64 s[24:25], v7, v6
	v_cndmask_b32_e64 v40, v0, v1, s[8:9]
	v_cndmask_b32_e64 v44, 0, 1, s[8:9]
	v_cndmask_b32_e64 v141, v8, v9, s[8:9]
	v_cndmask_b32_e64 v41, v2, v3, s[10:11]
	v_cndmask_b32_e64 v45, 2, 3, s[10:11]
	v_cndmask_b32_e64 v142, v10, v11, s[10:11]
	v_cndmask_b32_e64 v42, v4, v5, s[12:13]
	v_cndmask_b32_e64 v46, 4, 5, s[12:13]
	v_cndmask_b32_e64 v143, v12, v13, s[12:13]
	v_cndmask_b32_e64 v43, v6, v7, s[24:25]
	v_cndmask_b32_e64 v47, 6, 7, s[24:25]
	v_cndmask_b32_e64 v144, v14, v15, s[24:25]
	v_cmp_gt_f32_e64 s[8:9], v41, v40
	v_cmp_gt_f32_e64 s[10:11], v43, v42
	s_nop 0
	v_cndmask_b32_e64 v40, v40, v41, s[8:9]
	v_cndmask_b32_e64 v44, v44, v45, s[8:9]
	v_cndmask_b32_e64 v141, v141, v142, s[8:9]
	v_cndmask_b32_e64 v42, v42, v43, s[10:11]
	v_cndmask_b32_e64 v46, v46, v47, s[10:11]
	v_cndmask_b32_e64 v143, v143, v144, s[10:11]
	v_cmp_gt_f32_e64 s[8:9], v42, v40
	s_nop 1
	v_cndmask_b32_e64 v40, v40, v42, s[8:9]
	v_cndmask_b32_e64 v44, v44, v46, s[8:9]
	v_cndmask_b32_e64 v141, v141, v143, s[8:9]
	ds_write_b32 v55, v40 offset:48
	ds_write_b8 v57, v141 offset:12
	v_lshl_add_u32 v146, v141, 2, v54
	ds_write_b32 v146, v60
	v_lshl_add_u32 v147, v44, 6, v54
	ds_read2_b32 v[16:17], v147 offset0:0 offset1:1
	ds_read2_b32 v[18:19], v147 offset0:2 offset1:3
	ds_read2_b32 v[20:21], v147 offset0:4 offset1:5
	ds_read2_b32 v[22:23], v147 offset0:6 offset1:7
	ds_read2_b32 v[24:25], v147 offset0:8 offset1:9
	ds_read2_b32 v[26:27], v147 offset0:10 offset1:11
	ds_read2_b32 v[28:29], v147 offset0:12 offset1:13
	ds_read2_b32 v[30:31], v147 offset0:14 offset1:15
	s_waitcnt lgkmcnt(0)
; DI void peer_topk_item(const Params& p, int tt128, int head, char* smem) {
;     ...
; #pragma unroll 1
;     for (int r = 0; r < 16; ++r) {
;       float best = gm[0]; int bg = 0; int bi = gi[0];
; #pragma unroll
;       for (int g = 1; g < 8; ++g) if (gm[g] > best) { best = gm[g]; bg = g; bi = gi[g]; }
;       topv[tid * 16 + r] = best; topi[tid * 16 + r] = (unsigned char)bi;
;       row[bi] = -INFINITY;
;       float m = -INFINITY; int mi = bg * 16;
; #pragma unroll
;       for (int j = 0; j < 16; ++j) { float v = row[bg * 16 + j]; if (v > m) { m = v; mi = bg * 16 + j; } }
; #pragma unroll
;       for (int g = 0; g < 8; ++g) { gm[g] = (g == bg) ? m : gm[g]; gi[g] = (g == bg) ? mi : gi[g]; }
;     }
	v_cmp_gt_f32_e64 s[8:9], v17, v16
	v_cmp_gt_f32_e64 s[10:11], v19, v18
	v_cmp_gt_f32_e64 s[12:13], v21, v20
	v_cmp_gt_f32_e64 s[24:25], v23, v22
	v_cmp_gt_f32_e64 s[26:27], v25, v24
	v_cmp_gt_f32_e64 s[28:29], v27, v26
	v_cmp_gt_f32_e64 s[30:31], v29, v28
	v_cmp_gt_f32_e64 s[34:35], v31, v30
	v_cndmask_b32_e64 v16, v16, v17, s[8:9]
	v_cndmask_b32_e64 v32, 0, 1, s[8:9]
	v_cndmask_b32_e64 v18, v18, v19, s[10:11]
	v_cndmask_b32_e64 v33, 2, 3, s[10:11]
	v_cndmask_b32_e64 v20, v20, v21, s[12:13]
	v_cndmask_b32_e64 v34, 4, 5, s[12:13]
	v_cndmask_b32_e64 v22, v22, v23, s[24:25]
	v_cndmask_b32_e64 v35, 6, 7, s[24:25]
	v_cndmask_b32_e64 v24, v24, v25, s[26:27]
	v_cndmask_b32_e64 v36, 8, 9, s[26:27]
	v_cndmask_b32_e64 v26, v26, v27, s[28:29]
	v_cndmask_b32_e64 v37, 10, 11, s[28:29]
	v_cndmask_b32_e64 v28, v28, v29, s[30:31]
	v_cndmask_b32_e64 v38, 12, 13, s[30:31]
	v_cndmask_b32_e64 v30, v30, v31, s[34:35]
	v_cndmask_b32_e64 v39, 14, 15, s[34:35]
	v_cmp_gt_f32_e64 s[8:9], v18, v16
	v_cmp_gt_f32_e64 s[10:11], v22, v20
	v_cmp_gt_f32_e64 s[12:13], v26, v24
	v_cmp_gt_f32_e64 s[24:25], v30, v28
	v_cndmask_b32_e64 v16, v16, v18, s[8:9]
	v_cndmask_b32_e64 v32, v32, v33, s[8:9]
	v_cndmask_b32_e64 v20, v20, v22, s[10:11]
	v_cndmask_b32_e64 v34, v34, v35, s[10:11]
	v_cndmask_b32_e64 v24, v24, v26, s[12:13]
	v_cndmask_b32_e64 v36, v36, v37, s[12:13]
	v_cndmask_b32_e64 v28, v28, v30, s[24:25]
	v_cndmask_b32_e64 v38, v38, v39, s[24:25]
	v_cmp_gt_f32_e64 s[8:9], v20, v16
	v_cmp_gt_f32_e64 s[10:11], v28, v24
	s_nop 0
	v_cndmask_b32_e64 v16, v16, v20, s[8:9]
	v_cndmask_b32_e64 v32, v32, v34, s[8:9]
	v_cndmask_b32_e64 v24, v24, v28, s[10:11]
	v_cndmask_b32_e64 v36, v36, v38, s[10:11]
	v_cmp_gt_f32_e64 s[8:9], v24, v16
	s_nop 1
	v_cndmask_b32_e64 v16, v16, v24, s[8:9]
	v_cndmask_b32_e64 v32, v32, v36, s[8:9]
	v_lshl_add_u32 v148, v44, 4, v32
	v_cmp_eq_u32_e64 s[8:9], 0, v44
	v_cmp_eq_u32_e64 s[10:11], 1, v44
	v_cmp_eq_u32_e64 s[12:13], 2, v44
	v_cmp_eq_u32_e64 s[24:25], 3, v44
	v_cmp_eq_u32_e64 s[26:27], 4, v44
	v_cmp_eq_u32_e64 s[28:29], 5, v44
	v_cmp_eq_u32_e64 s[30:31], 6, v44
	v_cmp_eq_u32_e64 s[34:35], 7, v44
	v_cndmask_b32_e64 v0, v0, v16, s[8:9]
	v_cndmask_b32_e64 v8, v8, v148, s[8:9]
	v_cndmask_b32_e64 v1, v1, v16, s[10:11]
	v_cndmask_b32_e64 v9, v9, v148, s[10:11]
	v_cndmask_b32_e64 v2, v2, v16, s[12:13]
	v_cndmask_b32_e64 v10, v10, v148, s[12:13]
	v_cndmask_b32_e64 v3, v3, v16, s[24:25]
	v_cndmask_b32_e64 v11, v11, v148, s[24:25]
	v_cndmask_b32_e64 v4, v4, v16, s[26:27]
	v_cndmask_b32_e64 v12, v12, v148, s[26:27]
	v_cndmask_b32_e64 v5, v5, v16, s[28:29]
	v_cndmask_b32_e64 v13, v13, v148, s[28:29]
	v_cndmask_b32_e64 v6, v6, v16, s[30:31]
	v_cndmask_b32_e64 v14, v14, v148, s[30:31]
	v_cndmask_b32_e64 v7, v7, v16, s[34:35]
	v_cndmask_b32_e64 v15, v15, v148, s[34:35]
	v_cmp_gt_f32_e64 s[8:9], v1, v0
	v_cmp_gt_f32_e64 s[10:11], v3, v2
	v_cmp_gt_f32_e64 s[12:13], v5, v4
	v_cmp_gt_f32_e64 s[24:25], v7, v6
	v_cndmask_b32_e64 v40, v0, v1, s[8:9]
	v_cndmask_b32_e64 v44, 0, 1, s[8:9]
	v_cndmask_b32_e64 v141, v8, v9, s[8:9]
	v_cndmask_b32_e64 v41, v2, v3, s[10:11]
	v_cndmask_b32_e64 v45, 2, 3, s[10:11]
	v_cndmask_b32_e64 v142, v10, v11, s[10:11]
	v_cndmask_b32_e64 v42, v4, v5, s[12:13]
	v_cndmask_b32_e64 v46, 4, 5, s[12:13]
	v_cndmask_b32_e64 v143, v12, v13, s[12:13]
	v_cndmask_b32_e64 v43, v6, v7, s[24:25]
	v_cndmask_b32_e64 v47, 6, 7, s[24:25]
	v_cndmask_b32_e64 v144, v14, v15, s[24:25]
	v_cmp_gt_f32_e64 s[8:9], v41, v40
	v_cmp_gt_f32_e64 s[10:11], v43, v42
	s_nop 0
	v_cndmask_b32_e64 v40, v40, v41, s[8:9]
	v_cndmask_b32_e64 v44, v44, v45, s[8:9]
	v_cndmask_b32_e64 v141, v141, v142, s[8:9]
	v_cndmask_b32_e64 v42, v42, v43, s[10:11]
	v_cndmask_b32_e64 v46, v46, v47, s[10:11]
	v_cndmask_b32_e64 v143, v143, v144, s[10:11]
	v_cmp_gt_f32_e64 s[8:9], v42, v40
	s_nop 1
	v_cndmask_b32_e64 v40, v40, v42, s[8:9]
	v_cndmask_b32_e64 v44, v44, v46, s[8:9]
	v_cndmask_b32_e64 v141, v141, v143, s[8:9]
	ds_write_b32 v55, v40 offset:52
	ds_write_b8 v57, v141 offset:13
	v_lshl_add_u32 v146, v141, 2, v54
	ds_write_b32 v146, v60
	v_lshl_add_u32 v147, v44, 6, v54
	ds_read2_b32 v[16:17], v147 offset0:0 offset1:1
	ds_read2_b32 v[18:19], v147 offset0:2 offset1:3
	ds_read2_b32 v[20:21], v147 offset0:4 offset1:5
	ds_read2_b32 v[22:23], v147 offset0:6 offset1:7
	ds_read2_b32 v[24:25], v147 offset0:8 offset1:9
	ds_read2_b32 v[26:27], v147 offset0:10 offset1:11
	ds_read2_b32 v[28:29], v147 offset0:12 offset1:13
	ds_read2_b32 v[30:31], v147 offset0:14 offset1:15
	s_waitcnt lgkmcnt(0)
; DI void peer_topk_item(const Params& p, int tt128, int head, char* smem) {
;     ...
; #pragma unroll 1
;     for (int r = 0; r < 16; ++r) {
;       float best = gm[0]; int bg = 0; int bi = gi[0];
; #pragma unroll
;       for (int g = 1; g < 8; ++g) if (gm[g] > best) { best = gm[g]; bg = g; bi = gi[g]; }
;       topv[tid * 16 + r] = best; topi[tid * 16 + r] = (unsigned char)bi;
;       row[bi] = -INFINITY;
;       float m = -INFINITY; int mi = bg * 16;
; #pragma unroll
;       for (int j = 0; j < 16; ++j) { float v = row[bg * 16 + j]; if (v > m) { m = v; mi = bg * 16 + j; } }
; #pragma unroll
;       for (int g = 0; g < 8; ++g) { gm[g] = (g == bg) ? m : gm[g]; gi[g] = (g == bg) ? mi : gi[g]; }
;     }
	v_cmp_gt_f32_e64 s[8:9], v17, v16
	v_cmp_gt_f32_e64 s[10:11], v19, v18
	v_cmp_gt_f32_e64 s[12:13], v21, v20
	v_cmp_gt_f32_e64 s[24:25], v23, v22
	v_cmp_gt_f32_e64 s[26:27], v25, v24
	v_cmp_gt_f32_e64 s[28:29], v27, v26
	v_cmp_gt_f32_e64 s[30:31], v29, v28
	v_cmp_gt_f32_e64 s[34:35], v31, v30
	v_cndmask_b32_e64 v16, v16, v17, s[8:9]
	v_cndmask_b32_e64 v32, 0, 1, s[8:9]
	v_cndmask_b32_e64 v18, v18, v19, s[10:11]
	v_cndmask_b32_e64 v33, 2, 3, s[10:11]
	v_cndmask_b32_e64 v20, v20, v21, s[12:13]
	v_cndmask_b32_e64 v34, 4, 5, s[12:13]
	v_cndmask_b32_e64 v22, v22, v23, s[24:25]
	v_cndmask_b32_e64 v35, 6, 7, s[24:25]
	v_cndmask_b32_e64 v24, v24, v25, s[26:27]
	v_cndmask_b32_e64 v36, 8, 9, s[26:27]
	v_cndmask_b32_e64 v26, v26, v27, s[28:29]
	v_cndmask_b32_e64 v37, 10, 11, s[28:29]
	v_cndmask_b32_e64 v28, v28, v29, s[30:31]
	v_cndmask_b32_e64 v38, 12, 13, s[30:31]
	v_cndmask_b32_e64 v30, v30, v31, s[34:35]
	v_cndmask_b32_e64 v39, 14, 15, s[34:35]
	v_cmp_gt_f32_e64 s[8:9], v18, v16
	v_cmp_gt_f32_e64 s[10:11], v22, v20
	v_cmp_gt_f32_e64 s[12:13], v26, v24
	v_cmp_gt_f32_e64 s[24:25], v30, v28
	v_cndmask_b32_e64 v16, v16, v18, s[8:9]
	v_cndmask_b32_e64 v32, v32, v33, s[8:9]
	v_cndmask_b32_e64 v20, v20, v22, s[10:11]
	v_cndmask_b32_e64 v34, v34, v35, s[10:11]
	v_cndmask_b32_e64 v24, v24, v26, s[12:13]
	v_cndmask_b32_e64 v36, v36, v37, s[12:13]
	v_cndmask_b32_e64 v28, v28, v30, s[24:25]
	v_cndmask_b32_e64 v38, v38, v39, s[24:25]
	v_cmp_gt_f32_e64 s[8:9], v20, v16
	v_cmp_gt_f32_e64 s[10:11], v28, v24
	s_nop 0
	v_cndmask_b32_e64 v16, v16, v20, s[8:9]
	v_cndmask_b32_e64 v32, v32, v34, s[8:9]
	v_cndmask_b32_e64 v24, v24, v28, s[10:11]
	v_cndmask_b32_e64 v36, v36, v38, s[10:11]
	v_cmp_gt_f32_e64 s[8:9], v24, v16
	s_nop 1
	v_cndmask_b32_e64 v16, v16, v24, s[8:9]
	v_cndmask_b32_e64 v32, v32, v36, s[8:9]
	v_lshl_add_u32 v148, v44, 4, v32
	v_cmp_eq_u32_e64 s[8:9], 0, v44
	v_cmp_eq_u32_e64 s[10:11], 1, v44
	v_cmp_eq_u32_e64 s[12:13], 2, v44
	v_cmp_eq_u32_e64 s[24:25], 3, v44
	v_cmp_eq_u32_e64 s[26:27], 4, v44
	v_cmp_eq_u32_e64 s[28:29], 5, v44
	v_cmp_eq_u32_e64 s[30:31], 6, v44
	v_cmp_eq_u32_e64 s[34:35], 7, v44
	v_cndmask_b32_e64 v0, v0, v16, s[8:9]
	v_cndmask_b32_e64 v8, v8, v148, s[8:9]
	v_cndmask_b32_e64 v1, v1, v16, s[10:11]
	v_cndmask_b32_e64 v9, v9, v148, s[10:11]
	v_cndmask_b32_e64 v2, v2, v16, s[12:13]
	v_cndmask_b32_e64 v10, v10, v148, s[12:13]
	v_cndmask_b32_e64 v3, v3, v16, s[24:25]
	v_cndmask_b32_e64 v11, v11, v148, s[24:25]
	v_cndmask_b32_e64 v4, v4, v16, s[26:27]
	v_cndmask_b32_e64 v12, v12, v148, s[26:27]
	v_cndmask_b32_e64 v5, v5, v16, s[28:29]
	v_cndmask_b32_e64 v13, v13, v148, s[28:29]
	v_cndmask_b32_e64 v6, v6, v16, s[30:31]
	v_cndmask_b32_e64 v14, v14, v148, s[30:31]
	v_cndmask_b32_e64 v7, v7, v16, s[34:35]
	v_cndmask_b32_e64 v15, v15, v148, s[34:35]
	v_cmp_gt_f32_e64 s[8:9], v1, v0
	v_cmp_gt_f32_e64 s[10:11], v3, v2
	v_cmp_gt_f32_e64 s[12:13], v5, v4
	v_cmp_gt_f32_e64 s[24:25], v7, v6
	v_cndmask_b32_e64 v40, v0, v1, s[8:9]
	v_cndmask_b32_e64 v44, 0, 1, s[8:9]
	v_cndmask_b32_e64 v141, v8, v9, s[8:9]
	v_cndmask_b32_e64 v41, v2, v3, s[10:11]
	v_cndmask_b32_e64 v45, 2, 3, s[10:11]
	v_cndmask_b32_e64 v142, v10, v11, s[10:11]
	v_cndmask_b32_e64 v42, v4, v5, s[12:13]
	v_cndmask_b32_e64 v46, 4, 5, s[12:13]
	v_cndmask_b32_e64 v143, v12, v13, s[12:13]
	v_cndmask_b32_e64 v43, v6, v7, s[24:25]
	v_cndmask_b32_e64 v47, 6, 7, s[24:25]
	v_cndmask_b32_e64 v144, v14, v15, s[24:25]
	v_cmp_gt_f32_e64 s[8:9], v41, v40
	v_cmp_gt_f32_e64 s[10:11], v43, v42
	s_nop 0
	v_cndmask_b32_e64 v40, v40, v41, s[8:9]
	v_cndmask_b32_e64 v44, v44, v45, s[8:9]
	v_cndmask_b32_e64 v141, v141, v142, s[8:9]
	v_cndmask_b32_e64 v42, v42, v43, s[10:11]
	v_cndmask_b32_e64 v46, v46, v47, s[10:11]
	v_cndmask_b32_e64 v143, v143, v144, s[10:11]
	v_cmp_gt_f32_e64 s[8:9], v42, v40
	s_nop 1
	v_cndmask_b32_e64 v40, v40, v42, s[8:9]
	v_cndmask_b32_e64 v44, v44, v46, s[8:9]
	v_cndmask_b32_e64 v141, v141, v143, s[8:9]
	ds_write_b32 v55, v40 offset:56
	ds_write_b8 v57, v141 offset:14
	v_lshl_add_u32 v146, v141, 2, v54
	ds_write_b32 v146, v60
	v_lshl_add_u32 v147, v44, 6, v54
	ds_read2_b32 v[16:17], v147 offset0:0 offset1:1
	ds_read2_b32 v[18:19], v147 offset0:2 offset1:3
	ds_read2_b32 v[20:21], v147 offset0:4 offset1:5
	ds_read2_b32 v[22:23], v147 offset0:6 offset1:7
	ds_read2_b32 v[24:25], v147 offset0:8 offset1:9
	ds_read2_b32 v[26:27], v147 offset0:10 offset1:11
	ds_read2_b32 v[28:29], v147 offset0:12 offset1:13
	ds_read2_b32 v[30:31], v147 offset0:14 offset1:15
	s_waitcnt lgkmcnt(0)
; DI void peer_topk_item(const Params& p, int tt128, int head, char* smem) {
;     ...
; #pragma unroll 1
;     for (int r = 0; r < 16; ++r) {
;       float best = gm[0]; int bg = 0; int bi = gi[0];
; #pragma unroll
;       for (int g = 1; g < 8; ++g) if (gm[g] > best) { best = gm[g]; bg = g; bi = gi[g]; }
;       topv[tid * 16 + r] = best; topi[tid * 16 + r] = (unsigned char)bi;
;       row[bi] = -INFINITY;
;       float m = -INFINITY; int mi = bg * 16;
; #pragma unroll
;       for (int j = 0; j < 16; ++j) { float v = row[bg * 16 + j]; if (v > m) { m = v; mi = bg * 16 + j; } }
; #pragma unroll
;       for (int g = 0; g < 8; ++g) { gm[g] = (g == bg) ? m : gm[g]; gi[g] = (g == bg) ? mi : gi[g]; }
;     }
	v_cmp_gt_f32_e64 s[8:9], v17, v16
	v_cmp_gt_f32_e64 s[10:11], v19, v18
	v_cmp_gt_f32_e64 s[12:13], v21, v20
	v_cmp_gt_f32_e64 s[24:25], v23, v22
	v_cmp_gt_f32_e64 s[26:27], v25, v24
	v_cmp_gt_f32_e64 s[28:29], v27, v26
	v_cmp_gt_f32_e64 s[30:31], v29, v28
	v_cmp_gt_f32_e64 s[34:35], v31, v30
	v_cndmask_b32_e64 v16, v16, v17, s[8:9]
	v_cndmask_b32_e64 v32, 0, 1, s[8:9]
	v_cndmask_b32_e64 v18, v18, v19, s[10:11]
	v_cndmask_b32_e64 v33, 2, 3, s[10:11]
	v_cndmask_b32_e64 v20, v20, v21, s[12:13]
	v_cndmask_b32_e64 v34, 4, 5, s[12:13]
	v_cndmask_b32_e64 v22, v22, v23, s[24:25]
	v_cndmask_b32_e64 v35, 6, 7, s[24:25]
	v_cndmask_b32_e64 v24, v24, v25, s[26:27]
	v_cndmask_b32_e64 v36, 8, 9, s[26:27]
	v_cndmask_b32_e64 v26, v26, v27, s[28:29]
	v_cndmask_b32_e64 v37, 10, 11, s[28:29]
	v_cndmask_b32_e64 v28, v28, v29, s[30:31]
	v_cndmask_b32_e64 v38, 12, 13, s[30:31]
	v_cndmask_b32_e64 v30, v30, v31, s[34:35]
	v_cndmask_b32_e64 v39, 14, 15, s[34:35]
	v_cmp_gt_f32_e64 s[8:9], v18, v16
	v_cmp_gt_f32_e64 s[10:11], v22, v20
	v_cmp_gt_f32_e64 s[12:13], v26, v24
	v_cmp_gt_f32_e64 s[24:25], v30, v28
	v_cndmask_b32_e64 v16, v16, v18, s[8:9]
	v_cndmask_b32_e64 v32, v32, v33, s[8:9]
	v_cndmask_b32_e64 v20, v20, v22, s[10:11]
	v_cndmask_b32_e64 v34, v34, v35, s[10:11]
	v_cndmask_b32_e64 v24, v24, v26, s[12:13]
	v_cndmask_b32_e64 v36, v36, v37, s[12:13]
	v_cndmask_b32_e64 v28, v28, v30, s[24:25]
	v_cndmask_b32_e64 v38, v38, v39, s[24:25]
	v_cmp_gt_f32_e64 s[8:9], v20, v16
	v_cmp_gt_f32_e64 s[10:11], v28, v24
	s_nop 0
	v_cndmask_b32_e64 v16, v16, v20, s[8:9]
	v_cndmask_b32_e64 v32, v32, v34, s[8:9]
	v_cndmask_b32_e64 v24, v24, v28, s[10:11]
	v_cndmask_b32_e64 v36, v36, v38, s[10:11]
	v_cmp_gt_f32_e64 s[8:9], v24, v16
	s_nop 1
	v_cndmask_b32_e64 v16, v16, v24, s[8:9]
	v_cndmask_b32_e64 v32, v32, v36, s[8:9]
	v_lshl_add_u32 v148, v44, 4, v32
	v_cmp_eq_u32_e64 s[8:9], 0, v44
	v_cmp_eq_u32_e64 s[10:11], 1, v44
	v_cmp_eq_u32_e64 s[12:13], 2, v44
	v_cmp_eq_u32_e64 s[24:25], 3, v44
	v_cmp_eq_u32_e64 s[26:27], 4, v44
	v_cmp_eq_u32_e64 s[28:29], 5, v44
	v_cmp_eq_u32_e64 s[30:31], 6, v44
	v_cmp_eq_u32_e64 s[34:35], 7, v44
	v_cndmask_b32_e64 v0, v0, v16, s[8:9]
	v_cndmask_b32_e64 v8, v8, v148, s[8:9]
	v_cndmask_b32_e64 v1, v1, v16, s[10:11]
	v_cndmask_b32_e64 v9, v9, v148, s[10:11]
	v_cndmask_b32_e64 v2, v2, v16, s[12:13]
	v_cndmask_b32_e64 v10, v10, v148, s[12:13]
	v_cndmask_b32_e64 v3, v3, v16, s[24:25]
	v_cndmask_b32_e64 v11, v11, v148, s[24:25]
	v_cndmask_b32_e64 v4, v4, v16, s[26:27]
	v_cndmask_b32_e64 v12, v12, v148, s[26:27]
	v_cndmask_b32_e64 v5, v5, v16, s[28:29]
	v_cndmask_b32_e64 v13, v13, v148, s[28:29]
	v_cndmask_b32_e64 v6, v6, v16, s[30:31]
	v_cndmask_b32_e64 v14, v14, v148, s[30:31]
	v_cndmask_b32_e64 v7, v7, v16, s[34:35]
	v_cndmask_b32_e64 v15, v15, v148, s[34:35]
	v_cmp_gt_f32_e64 s[8:9], v1, v0
	v_cmp_gt_f32_e64 s[10:11], v3, v2
	v_cmp_gt_f32_e64 s[12:13], v5, v4
	v_cmp_gt_f32_e64 s[24:25], v7, v6
	v_cndmask_b32_e64 v40, v0, v1, s[8:9]
	v_cndmask_b32_e64 v44, 0, 1, s[8:9]
	v_cndmask_b32_e64 v141, v8, v9, s[8:9]
	v_cndmask_b32_e64 v41, v2, v3, s[10:11]
	v_cndmask_b32_e64 v45, 2, 3, s[10:11]
	v_cndmask_b32_e64 v142, v10, v11, s[10:11]
	v_cndmask_b32_e64 v42, v4, v5, s[12:13]
	v_cndmask_b32_e64 v46, 4, 5, s[12:13]
	v_cndmask_b32_e64 v143, v12, v13, s[12:13]
	v_cndmask_b32_e64 v43, v6, v7, s[24:25]
	v_cndmask_b32_e64 v47, 6, 7, s[24:25]
	v_cndmask_b32_e64 v144, v14, v15, s[24:25]
	v_cmp_gt_f32_e64 s[8:9], v41, v40
	v_cmp_gt_f32_e64 s[10:11], v43, v42
	s_nop 0
	v_cndmask_b32_e64 v40, v40, v41, s[8:9]
	v_cndmask_b32_e64 v44, v44, v45, s[8:9]
	v_cndmask_b32_e64 v141, v141, v142, s[8:9]
	v_cndmask_b32_e64 v42, v42, v43, s[10:11]
	v_cndmask_b32_e64 v46, v46, v47, s[10:11]
	v_cndmask_b32_e64 v143, v143, v144, s[10:11]
	v_cmp_gt_f32_e64 s[8:9], v42, v40
	s_nop 1
	v_cndmask_b32_e64 v40, v40, v42, s[8:9]
	v_cndmask_b32_e64 v44, v44, v46, s[8:9]
	v_cndmask_b32_e64 v141, v141, v143, s[8:9]
	ds_write_b32 v55, v40 offset:60
	ds_write_b8 v57, v141 offset:15
	v_readlane_b32 s20, v255, 5
	v_readlane_b32 s21, v255, 6
	s_waitcnt lgkmcnt(0)
